# GEMM unit boundaries: layer-1 in-projection rstd values and out-projection SSQ rows fetched one unit ahead (no dependent load + vmcnt(0) at the epilogue / unit start)
# speedup vs baseline: 1.0014x; 1.0014x over previous
; #define PG8_STAGE(bufoff, gbase, voff) do { _Pragma("unroll") for (int _i = 0; _i < 2; ++_i) \
;         __builtin_amdgcn_global_load_lds((const unsigned*)((const char*)(gbase) + (voff)[_i]), (PG8_LAS unsigned*)(lds + (bufoff) + ldsw + _i * 8192), 16, 0, 0); } while (0)
; #define PG8_WAIT_V(n) asm volatile("s_waitcnt vmcnt(" #n ")" ::: "memory")
; #define PG8_BAR __builtin_amdgcn_s_barrier()
; template <class Epi, class Sched, bool ALIGN_EPI = false, bool SP2 = false>
; __device__ __forceinline__ void gemm_phase(PG8_LAS unsigned char* lds, const Gemm g, const Sched& S, const Epi& E) {
;     ...
;     for (int i = 0; i < 2; ++i) { int R, C; stage_rc(tid * 16 + i * 8192, R, C); const int Rb = Epi::PERM ? ((R & ~31) + perm32(R & 31)) : R;
;         voffA[i] = (unsigned)(R * K + C) * 2u; voffB[i] = (unsigned)(Rb * K + C) * 2u; }
;     const size_t kstep = (size_t)(BK * 2);
;     const size_t hstep = (size_t)HALF * K * 2;
;     const size_t tstep = 2 * hstep;
;     const unsigned ldsw = (unsigned)wid * 1024u;
;     const int aoff = lds_byte(wr * 64 + fr, fq * 8), boff = lds_byte(wc * 32 + fr, fq * 8);
;     ...
;         PG8_STAGE(PG8_SB(1, 0), cB + kstep, voffB); PG8_STAGE(PG8_SA(1, 0), cA + kstep, voffA); PG8_STAGE(PG8_SB(1, 1), cB + hstep + kstep, voffB);
;         PG8_WAIT_V(6); PG8_BAR;
;     } else {
;         PG8_STAGE(PG8_SB(0, 0), cB, voffB); PG8_STAGE(PG8_SA(0, 0), cA, voffA); PG8_STAGE(PG8_SB(0, 1), cB + hstep, voffB); PG8_STAGE(PG8_SA(0, 1), cA + hstep, voffA);
;         if (wr == 1) PG8_BAR;
;         PG8_WAIT_V(4); PG8_BAR;
;         PG8_STAGE(PG8_SB(1, 0), cB + kstep, voffB); PG8_STAGE(PG8_SA(1, 0), cA + kstep, voffA); PG8_STAGE(PG8_SB(1, 1), cB + hstep + kstep, voffB);
;         PG8_WAIT_V(6); PG8_BAR;
;     }
.LBB0_631:
	s_lshl_b32 s7, s7, 5
	s_mov_b64 s[18:19], 0x80
	s_and_b32 s7, s7, 0x60
	s_add_i32 m0, s62, 0x18000
	v_lshl_add_u64 v[10:11], v[10:11], 0, s[18:19]
	s_lshl_b32 s22, s5, 6
	s_lshl_b32 s5, s5, 13
	s_lshl_b32 s20, s7, 7
	s_waitcnt vmcnt(2)
	s_barrier
	global_load_lds_dwordx4 v[10:11], off
	v_lshl_add_u64 v[8:9], v[8:9], 0, s[18:19]
	s_add_i32 m0, s62, 0x1a000
	s_add_i32 s67, s62, 0x8000
	s_add_i32 s68, s62, 0xa000
	global_load_lds_dwordx4 v[8:9], off
	v_lshl_add_u64 v[4:5], v[4:5], 0, s[18:19]
	s_mov_b32 m0, s67
	s_add_u32 s8, s2, 0x40080
	global_load_lds_dwordx4 v[4:5], off
	v_lshl_add_u64 v[4:5], v[6:7], 0, s[18:19]
	s_mov_b32 m0, s68
	s_addc_u32 s9, s3, 0
	global_load_lds_dwordx4 v[4:5], off
	s_add_i32 m0, s62, 0x1c000
	v_lshl_add_u64 v[4:5], s[8:9], 0, v[136:137]
	global_load_lds_dwordx4 v[4:5], off
	v_lshl_add_u64 v[4:5], s[8:9], 0, v[140:141]
	s_add_i32 m0, s62, 0x1e000
	s_cmpk_lt_u32 s6, 0x100
	global_load_lds_dwordx4 v[4:5], off
	v_lshrrev_b32_e32 v5, 1, v1
	v_and_b32_e32 v5, 24, v5
	v_and_b32_e32 v4, 15, v1
	v_lshlrev_b32_e32 v6, 1, v5
	v_lshlrev_b32_e32 v1, 2, v1
	v_or_b32_e32 v142, s22, v4
	v_lshl_or_b32 v4, v4, 6, v6
	v_and_b32_e32 v1, 32, v1
	v_bitop3_b32 v6, v4, s5, v1 bitop3:0xde
	v_bitop3_b32 v1, v4, s20, v1 bitop3:0xde
	s_cselect_b64 s[20:21], -1, 0
	s_ashr_i32 s6, s22, 31
	v_mov_b32_e32 v143, s6
	v_lshlrev_b32_e32 v4, 14, v14
	v_lshlrev_b64 v[144:145], 10, v[142:143]
	v_and_b32_e32 v4, 0xffff8000, v4
	v_or3_b32 v144, s7, v5, v144
	v_lshl_add_u32 v4, v15, 11, v4
	v_and_b32_e32 v5, 1, v14
	v_lshl_or_b32 v4, v5, 6, v4
	s_mov_b64 s[8:9], 0x40080
	v_lshl_add_u32 v4, v16, 1, v4
	v_mov_b32_e32 v5, v2
	v_lshl_add_u64 v[146:147], v[4:5], 0, s[8:9]
	v_lshlrev_b32_e32 v4, 14, v3
	v_and_b32_e32 v4, 0xffff8000, v4
	v_lshl_add_u32 v4, v12, 11, v4
	v_and_b32_e32 v3, 1, v3
	s_waitcnt vmcnt(6)
	v_lshl_or_b32 v3, v3, 6, v4
	s_sext_i32_i8 s83, s4
	s_movk_i32 s4, 0x100
	v_lshl_add_u32 v4, v13, 1, v3
	v_cmp_gt_u32_e64 s[4:5], s4, v0
	s_ashr_i32 s69, s33, 31
	v_lshl_add_u64 v[148:149], v[4:5], 0, s[8:9]
	v_mov_b32_e32 v143, 0x358637bd
	s_mov_b32 s70, 0xf800000
	v_mov_b32_e32 v158, 0x260
	s_add_i32 s71, 0, 0x10000
	s_add_i32 s72, 0, 0x14000
	v_add_u32_e32 v159, 0, v6
	s_mov_b32 s73, 0x30000
	s_mov_b64 s[22:23], 0x30200
	s_mov_b64 s[24:25], 0x80000
	s_mov_b32 s74, 0x80000
	s_mov_b64 s[26:27], 0x80200
	s_mov_b64 s[28:29], 0x90000
	s_mov_b32 s75, 0x90000
	s_mov_b64 s[30:31], 0x90200
	s_mov_b64 s[34:35], 0xa0000
	s_mov_b32 s76, 0xa0000
	s_mov_b64 s[36:37], 0xa0200
	s_mov_b64 s[38:39], 0xb0000
	s_mov_b32 s77, 0xb0000
	s_mov_b64 s[40:41], 0xb0200
	s_mov_b32 s78, 0x40000
	s_mov_b32 s79, 0x48000
	s_mov_b32 s80, 0x50000
	s_mov_b32 s81, 0x58000
	v_mov_b64_e32 v[150:151], 0x400
	v_mov_b64_e32 v[152:153], 0x3ff
	s_barrier
	s_mov_b32 s93, 0
	s_branch .LBB0_634

; #define LAS __attribute__((address_space(3)))
;     __device__ __forceinline__ void begin(const pg8::Unit& u, int ui) const {
;         const int tid = threadIdx.x;
;         if (tid < 256) {
;             const float* sq = ssq + (size_t)(u.pm * 256 + tid) * 16;
;             const pg8::f32x4 a0 = *(const pg8::f32x4*)sq, a1 = *(const pg8::f32x4*)(sq + 4), b0 = *(const pg8::f32x4*)(sq + 8), b1 = *(const pg8::f32x4*)(sq + 12);
;             const float sa = ((a0[0] + a0[1]) + (a0[2] + a0[3])) + ((a1[0] + a1[1]) + (a1[2] + a1[3]));
;             const float sb = ((b0[0] + b0[1]) + (b0[2] + b0[3])) + ((b1[0] + b1[1]) + (b1[2] + b1[3]));
;             const float rA = 1.0f / sqrtf(sa * (1.0f / W) + EPS), rB = 1.0f / sqrtf(sb * (1.0f / W) + EPS);
;             LAS float* t = tab + ((ui & 1) * 256 + tid) * 2; t[0] = rA / rB; t[1] = rB;
;         }
.LBB0_633:
	s_mov_b32 s93, 1
	s_andn2_b64 vcc, exec, s[2:3]
	s_mov_b32 s83, s42
	s_mov_b32 s48, s44
	s_mov_b64 s[2:3], s[46:47]
	s_mov_b64 s[50:51], s[8:9]
	s_mov_b32 s52, s82
	s_cbranch_vccz .LBB0_651
.LBB0_634:
	s_and_saveexec_b64 s[46:47], s[4:5]
	s_cbranch_execz .LBB0_636
	v_lshl_or_b32 v4, s48, 8, v0
	v_ashrrev_i32_e32 v5, 31, v4
	v_lshlrev_b64 v[4:5], 6, v[4:5]
	v_lshl_add_u64 v[16:17], s[10:11], 0, v[4:5]
	s_cmp_lg_u32 s93, 0
	s_cbranch_scc1 .Lob_pipe_l0
	global_load_dwordx4 v[238:241], v[16:17], off
	global_load_dwordx4 v[244:247], v[16:17], off offset:16
	global_load_dwordx4 v[248:251], v[16:17], off offset:32
	global_load_dwordx4 v[252:255], v[16:17], off offset:48
	s_waitcnt vmcnt(0)
.Lob_pipe_l0:
	s_lshl_b32 s6, s52, 8
	s_and_b32 s6, s6, 0x100
	v_or_b32_e32 v3, s6, v0
	v_lshl_add_u32 v3, v3, 3, 0
	v_add_u32_e32 v3, 0x20400, v3
	v_add_f32_e32 v4, v238, v239
	v_add_f32_e32 v5, v240, v241
	v_add_f32_e32 v6, v244, v245
	v_add_f32_e32 v7, v246, v247
	v_add_f32_e32 v8, v248, v249
	v_add_f32_e32 v9, v250, v251
	v_add_f32_e32 v10, v252, v253
	v_add_f32_e32 v11, v254, v255
	v_add_f32_e32 v4, v4, v5
	v_add_f32_e32 v5, v6, v7
	v_add_f32_e32 v6, v8, v9
	v_add_f32_e32 v7, v10, v11
	v_add_f32_e32 v4, v4, v5
	v_add_f32_e32 v5, v6, v7
	v_fmamk_f32 v4, v4, 0x3b000000, v143
	v_fmamk_f32 v5, v5, 0x3b000000, v143
	v_mul_f32_e32 v6, 0x4f800000, v4
	v_cmp_gt_f32_e32 vcc, s70, v4
	v_mul_f32_e32 v7, 0x4f800000, v5
	v_cmp_gt_f32_e64 s[6:7], s70, v5
	v_cndmask_b32_e32 v4, v4, v6, vcc
	v_sqrt_f32_e32 v6, v4
	v_cndmask_b32_e64 v5, v5, v7, s[6:7]
	v_sqrt_f32_e32 v7, v5
	v_add_u32_e32 v8, -1, v6
	v_fma_f32 v12, -v8, v6, v4
	v_add_u32_e32 v10, -1, v7
	v_add_u32_e32 v9, 1, v6
	v_fma_f32 v14, -v10, v7, v5
	v_cmp_ge_f32_e64 s[8:9], 0, v12
	v_add_u32_e32 v11, 1, v7
	v_fma_f32 v13, -v9, v6, v4
	v_cndmask_b32_e64 v6, v6, v8, s[8:9]
	v_cmp_ge_f32_e64 s[8:9], 0, v14
	v_fma_f32 v15, -v11, v7, v5
	s_nop 0
	v_cndmask_b32_e64 v7, v7, v10, s[8:9]
	v_cmp_lt_f32_e64 s[8:9], 0, v13
	s_nop 1
	v_cndmask_b32_e64 v6, v6, v9, s[8:9]
	v_cmp_lt_f32_e64 s[8:9], 0, v15
	v_mul_f32_e32 v8, 0x37800000, v6
	v_cndmask_b32_e32 v6, v6, v8, vcc
	v_cndmask_b32_e64 v7, v7, v11, s[8:9]
	v_mul_f32_e32 v9, 0x37800000, v7
	v_cmp_class_f32_e32 vcc, v4, v158
	v_cndmask_b32_e64 v7, v7, v9, s[6:7]
	s_nop 0
	v_cndmask_b32_e32 v4, v6, v4, vcc
	v_cmp_class_f32_e32 vcc, v5, v158
	v_div_scale_f32 v6, s[6:7], v4, v4, 1.0
	s_nop 0
	v_cndmask_b32_e32 v5, v7, v5, vcc
	v_div_scale_f32 v8, s[6:7], v5, v5, 1.0
	v_rcp_f32_e32 v9, v6
	v_rcp_f32_e32 v10, v8
	v_div_scale_f32 v7, vcc, 1.0, v4, 1.0
	v_fma_f32 v12, -v6, v9, 1.0
	v_fma_f32 v13, -v8, v10, 1.0
	v_fmac_f32_e32 v9, v12, v9
	v_div_scale_f32 v11, s[6:7], 1.0, v5, 1.0
	v_fmac_f32_e32 v10, v13, v10
	v_mul_f32_e32 v12, v7, v9
	v_mul_f32_e32 v13, v11, v10
	v_fma_f32 v14, -v6, v12, v7
	v_fma_f32 v15, -v8, v13, v11
	v_fmac_f32_e32 v12, v14, v9
	v_fmac_f32_e32 v13, v15, v10
	v_fma_f32 v6, -v6, v12, v7
	v_fma_f32 v7, -v8, v13, v11
	v_div_fmas_f32 v6, v6, v9, v12
	s_mov_b64 vcc, s[6:7]
	v_div_fixup_f32 v4, v6, v4, 1.0
	v_div_fmas_f32 v6, v7, v10, v13
	v_div_fixup_f32 v5, v6, v5, 1.0
	v_div_scale_f32 v6, s[6:7], v5, v5, v4
	v_rcp_f32_e32 v7, v6
	v_div_scale_f32 v8, vcc, v4, v5, v4
	v_fma_f32 v9, -v6, v7, 1.0
	v_fmac_f32_e32 v7, v9, v7
	v_mul_f32_e32 v9, v8, v7
	v_fma_f32 v10, -v6, v9, v8
	v_fmac_f32_e32 v9, v10, v7
	v_fma_f32 v6, -v6, v9, v8
	v_div_fmas_f32 v6, v6, v7, v9
	v_div_fixup_f32 v4, v6, v5, v4
	ds_write_b64 v3, v[4:5]

; #define LAS __attribute__((address_space(3)))
; __device__ __forceinline__ float bflo(unsigned w) { return __uint_as_float(w << 16); }
; __device__ __forceinline__ float bfhi(unsigned w) { return __uint_as_float(w & 0xffff0000u); }
; __device__ __forceinline__ unsigned cvt_pk_bf16(float lo, float hi) { unsigned r; asm volatile("v_cvt_pk_bf16_f32 %0, %1, %2" : "=v"(r) : "v"(lo), "v"(hi)); return r; }
;     __device__ __forceinline__ void operator()(const pg8::f32x4 (&acc)[2][2][4][2], const pg8::Unit& u, int ui, int wr, int wc, int fr, int fq) const {
;         const size_t off0 = ((size_t)u.pm * 256 + wr * 64 + fr) * D + u.pn * 256 + wc * 32 + 8 * fq;
;         const LAS float* tb = tab + ((ui & 1) * 256 + wr * 64 + fr) * 2 + 1;
;         bf16* xb = (bf16*)xp;
; #pragma unroll
;         for (int ai = 0; ai < 2; ++ai) {
;             pg8::f32x4 x[4][2][2];
; #pragma unroll
;             for (int m = 0; m < 4; ++m) { const size_t ro = off0 + (size_t)(ai * 128 + m * 16) * D;
; #pragma unroll
;                 for (int bj = 0; bj < 2; ++bj) {
;                     if (l == 0) { x[m][bj][0] = *(const pg8::f32x4*)(xin_p + ro + bj * 128); x[m][bj][1] = *(const pg8::f32x4*)(xin_p + ro + bj * 128 + 4); }
;                     else { const u32x4 w = *(const u32x4*)(xb + ro + bj * 128);
;                            x[m][bj][0] = (pg8::f32x4){bflo(w.x), bfhi(w.x), bflo(w.y), bfhi(w.y)}; x[m][bj][1] = (pg8::f32x4){bflo(w.z), bfhi(w.z), bflo(w.w), bfhi(w.w)}; } } }
; #pragma unroll
;             for (int m = 0; m < 4; ++m) { const size_t ro = off0 + (size_t)(ai * 128 + m * 16) * D; const float rB = tb[(ai * 128 + m * 16) * 2];
; #pragma unroll
;                 for (int bj = 0; bj < 2; ++bj) {
;                     const pg8::f32x4 y0 = x[m][bj][0] + acc[ai][bj][m][0] * rB, y1 = x[m][bj][1] + acc[ai][bj][m][1] * rB;
;                     u32x4 o; o.x = pg8::cvt_pk_bf16(y0[0], y0[1]); o.y = pg8::cvt_pk_bf16(y0[2], y0[3]); o.z = pg8::cvt_pk_bf16(y1[0], y1[1]); o.w = pg8::cvt_pk_bf16(y1[2], y1[3]);
;                     *(u32x4*)(xb + ro + bj * 128) = o; } }
.LBB0_648:
	s_and_saveexec_b64 s[94:95], s[4:5]
	v_lshl_or_b32 v234, s44, 8, v0
	v_ashrrev_i32_e32 v235, 31, v234
	v_lshlrev_b64 v[234:235], 6, v[234:235]
	v_lshl_add_u64 v[234:235], s[10:11], 0, v[234:235]
	global_load_dwordx4 v[238:241], v[234:235], off
	global_load_dwordx4 v[244:247], v[234:235], off offset:16
	global_load_dwordx4 v[248:251], v[234:235], off offset:32
	global_load_dwordx4 v[252:255], v[234:235], off offset:48
	s_mov_b64 exec, s[94:95]
	s_nop 1
	s_ashr_i32 s49, s48, 31
	s_lshl_b32 s43, s83, 8
	s_lshl_b64 s[2:3], s[48:49], 18
	s_ashr_i32 s45, s43, 31
	s_add_u32 s2, s2, s43
	s_addc_u32 s3, s3, s45
	v_lshl_add_u64 v[4:5], s[2:3], 0, v[144:145]
	v_lshl_add_u64 v[154:155], v[4:5], 2, s[12:13]
	global_load_dwordx4 v[162:165], v[154:155], off
	global_load_dwordx4 v[166:169], v[154:155], off offset:16
	global_load_dwordx4 v[170:173], v[154:155], off offset:512
	global_load_dwordx4 v[174:177], v[154:155], off offset:528
	s_mov_b64 s[2:3], 0x10000
	v_add_co_u32_e32 v156, vcc, s66, v154
	v_lshl_add_u64 v[182:183], v[154:155], 0, s[2:3]
	s_nop 0
	v_addc_co_u32_e32 v157, vcc, 0, v155, vcc
	s_mov_b64 s[2:3], 0x10200
	global_load_dwordx4 v[178:181], v[156:157], off
	s_nop 0
	global_load_dwordx4 v[182:185], v[182:183], off offset:16
	s_mov_b32 s43, 0x20000
	global_load_dwordx4 v[186:189], v[156:157], off offset:512
	v_lshl_add_u64 v[156:157], v[154:155], 0, s[2:3]
	global_load_dwordx4 v[190:193], v[156:157], off offset:16
	v_add_co_u32_e32 v156, vcc, s43, v154
	s_mov_b64 s[2:3], 0x20000
	s_nop 0
	v_addc_co_u32_e32 v157, vcc, 0, v155, vcc
	global_load_dwordx4 v[194:197], v[156:157], off
	global_load_dwordx4 v[202:205], v[156:157], off offset:512
	v_lshl_add_u64 v[198:199], v[154:155], 0, s[2:3]
	global_load_dwordx4 v[198:201], v[198:199], off offset:16
	s_mov_b64 s[2:3], 0x20200
	v_lshl_add_u64 v[156:157], v[154:155], 0, s[2:3]
	global_load_dwordx4 v[206:209], v[156:157], off offset:16
	s_mov_b64 s[2:3], 0x30000
	v_lshl_add_u64 v[214:215], v[154:155], 0, s[2:3]
	global_load_dwordx4 v[214:217], v[214:215], off offset:16
	v_add_co_u32_e32 v156, vcc, s73, v154
	s_add_i32 s45, 0, 0x20400
	s_nop 0
	v_addc_co_u32_e32 v157, vcc, 0, v155, vcc
	global_load_dwordx4 v[210:213], v[156:157], off
	v_add_u32_e32 v3, s45, v160
	v_lshl_add_u64 v[222:223], v[154:155], 0, s[22:23]
	ds_read_b32 v160, v3 offset:4
	global_load_dwordx4 v[218:221], v[156:157], off offset:512
	s_nop 0
	global_load_dwordx4 v[222:225], v[222:223], off offset:16
	v_lshl_add_u64 v[4:5], v[4:5], 1, s[16:17]
	s_mov_b32 s43, 0x8000
	s_mov_b32 s2, 0x18000
	v_readlane_b32 s84, v242, 6
	v_readlane_b32 s85, v242, 7
	s_waitcnt vmcnt(0) lgkmcnt(0)
	v_pk_fma_f32 v[132:133], v[132:133], v[160:161], v[164:165] op_sel_hi:[1,0,1]
	v_pk_fma_f32 v[130:131], v[130:131], v[160:161], v[162:163] op_sel_hi:[1,0,1]
	v_pk_fma_f32 v[128:129], v[128:129], v[160:161], v[168:169] op_sel_hi:[1,0,1]
	v_pk_fma_f32 v[126:127], v[126:127], v[160:161], v[166:167] op_sel_hi:[1,0,1]
	v_pk_fma_f32 v[124:125], v[124:125], v[160:161], v[172:173] op_sel_hi:[1,0,1]
	v_pk_fma_f32 v[122:123], v[122:123], v[160:161], v[170:171] op_sel_hi:[1,0,1]
	v_pk_fma_f32 v[156:157], v[120:121], v[160:161], v[176:177] op_sel_hi:[1,0,1]
	v_pk_fma_f32 v[160:161], v[118:119], v[160:161], v[174:175] op_sel_hi:[1,0,1]
	v_cvt_pk_bf16_f32 v118, v130, v131
	v_cvt_pk_bf16_f32 v119, v132, v133
	v_cvt_pk_bf16_f32 v120, v126, v127
	v_cvt_pk_bf16_f32 v121, v128, v129
	global_store_dwordx4 v[4:5], v[118:121], off
	v_lshl_add_u64 v[130:131], v[154:155], 0, s[40:41]
	s_nop 0
	v_cvt_pk_bf16_f32 v118, v122, v123
	v_cvt_pk_bf16_f32 v119, v124, v125
	v_cvt_pk_bf16_f32 v120, v160, v161
	v_cvt_pk_bf16_f32 v121, v156, v157
	ds_read_b32 v122, v3 offset:132
	v_add_co_u32_e32 v124, vcc, s43, v4
	global_store_dwordx4 v[4:5], v[118:121], off offset:256
	s_nop 0
	v_addc_co_u32_e32 v125, vcc, 0, v5, vcc
	s_waitcnt lgkmcnt(0)
	v_pk_fma_f32 v[116:117], v[116:117], v[122:123], v[180:181] op_sel_hi:[1,0,1]
	v_pk_fma_f32 v[114:115], v[114:115], v[122:123], v[178:179] op_sel_hi:[1,0,1]
	v_pk_fma_f32 v[112:113], v[112:113], v[122:123], v[184:185] op_sel_hi:[1,0,1]
	v_pk_fma_f32 v[110:111], v[110:111], v[122:123], v[182:183] op_sel_hi:[1,0,1]
	v_pk_fma_f32 v[106:107], v[106:107], v[122:123], v[186:187] op_sel_hi:[1,0,1]
	v_pk_fma_f32 v[118:119], v[104:105], v[122:123], v[192:193] op_sel_hi:[1,0,1]
	v_pk_fma_f32 v[120:121], v[102:103], v[122:123], v[190:191] op_sel_hi:[1,0,1]
	v_cvt_pk_bf16_f32 v102, v114, v115
	v_cvt_pk_bf16_f32 v103, v116, v117
	v_cvt_pk_bf16_f32 v104, v110, v111
	v_cvt_pk_bf16_f32 v105, v112, v113
	v_pk_fma_f32 v[108:109], v[108:109], v[122:123], v[188:189] op_sel_hi:[1,0,1]
	global_store_dwordx4 v[124:125], v[102:105], off
	v_lshl_add_u64 v[114:115], v[154:155], 0, s[36:37]
	v_lshl_add_u64 v[122:123], v[154:155], 0, s[38:39]
	v_cvt_pk_bf16_f32 v102, v106, v107
	v_cvt_pk_bf16_f32 v103, v108, v109
	v_cvt_pk_bf16_f32 v104, v120, v121
	v_cvt_pk_bf16_f32 v105, v118, v119
	ds_read_b32 v106, v3 offset:260
	global_store_dwordx4 v[124:125], v[102:105], off offset:256
	s_waitcnt lgkmcnt(0)
; __device__ __forceinline__ float bflo(unsigned w) { return __uint_as_float(w << 16); }
; __device__ __forceinline__ float bfhi(unsigned w) { return __uint_as_float(w & 0xffff0000u); }
; __device__ __forceinline__ unsigned cvt_pk_bf16(float lo, float hi) { unsigned r; asm volatile("v_cvt_pk_bf16_f32 %0, %1, %2" : "=v"(r) : "v"(lo), "v"(hi)); return r; }
;     __device__ __forceinline__ void operator()(const pg8::f32x4 (&acc)[2][2][4][2], const pg8::Unit& u, int ui, int wr, int wc, int fr, int fq) const {
;     ...
;             for (int m = 0; m < 4; ++m) { const size_t ro = off0 + (size_t)(ai * 128 + m * 16) * D;
; #pragma unroll
;                 for (int bj = 0; bj < 2; ++bj) {
;                     if (l == 0) { x[m][bj][0] = *(const pg8::f32x4*)(xin_p + ro + bj * 128); x[m][bj][1] = *(const pg8::f32x4*)(xin_p + ro + bj * 128 + 4); }
;                     else { const u32x4 w = *(const u32x4*)(xb + ro + bj * 128);
;                            x[m][bj][0] = (pg8::f32x4){bflo(w.x), bfhi(w.x), bflo(w.y), bfhi(w.y)}; x[m][bj][1] = (pg8::f32x4){bflo(w.z), bfhi(w.z), bflo(w.w), bfhi(w.w)}; } } }
; #pragma unroll
;             for (int m = 0; m < 4; ++m) { const size_t ro = off0 + (size_t)(ai * 128 + m * 16) * D; const float rB = tb[(ai * 128 + m * 16) * 2];
; #pragma unroll
;                 for (int bj = 0; bj < 2; ++bj) {
;                     const pg8::f32x4 y0 = x[m][bj][0] + acc[ai][bj][m][0] * rB, y1 = x[m][bj][1] + acc[ai][bj][m][1] * rB;
;                     u32x4 o; o.x = pg8::cvt_pk_bf16(y0[0], y0[1]); o.y = pg8::cvt_pk_bf16(y0[2], y0[3]); o.z = pg8::cvt_pk_bf16(y1[0], y1[1]); o.w = pg8::cvt_pk_bf16(y1[2], y1[3]);
;                     *(u32x4*)(xb + ro + bj * 128) = o; } }
	v_pk_fma_f32 v[98:99], v[98:99], v[106:107], v[194:195] op_sel_hi:[1,0,1]
	v_pk_fma_f32 v[102:103], v[96:97], v[106:107], v[200:201] op_sel_hi:[1,0,1]
	v_pk_fma_f32 v[96:97], v[94:95], v[106:107], v[198:199] op_sel_hi:[1,0,1]
	v_cvt_pk_bf16_f32 v94, v98, v99
	v_add_co_u32_e32 v98, vcc, s66, v4
	v_pk_fma_f32 v[100:101], v[100:101], v[106:107], v[196:197] op_sel_hi:[1,0,1]
	s_nop 0
	v_addc_co_u32_e32 v99, vcc, 0, v5, vcc
	v_cvt_pk_bf16_f32 v95, v100, v101
	v_cvt_pk_bf16_f32 v96, v96, v97
	v_cvt_pk_bf16_f32 v97, v102, v103
	global_store_dwordx4 v[98:99], v[94:97], off
	v_pk_fma_f32 v[90:91], v[90:91], v[106:107], v[202:203] op_sel_hi:[1,0,1]
	v_pk_fma_f32 v[92:93], v[92:93], v[106:107], v[204:205] op_sel_hi:[1,0,1]
	v_pk_fma_f32 v[94:95], v[88:89], v[106:107], v[208:209] op_sel_hi:[1,0,1]
	v_pk_fma_f32 v[88:89], v[86:87], v[106:107], v[206:207] op_sel_hi:[1,0,1]
	v_cvt_pk_bf16_f32 v86, v90, v91
	v_cvt_pk_bf16_f32 v87, v92, v93
	v_lshl_add_u64 v[106:107], v[154:155], 0, s[34:35]
	v_cvt_pk_bf16_f32 v88, v88, v89
	v_cvt_pk_bf16_f32 v89, v94, v95
	ds_read_b32 v90, v3 offset:388
	global_store_dwordx4 v[98:99], v[86:89], off offset:256
	v_lshl_add_u64 v[98:99], v[154:155], 0, s[30:31]
	s_waitcnt lgkmcnt(0)
	v_pk_fma_f32 v[82:83], v[82:83], v[90:91], v[210:211] op_sel_hi:[1,0,1]
	v_pk_fma_f32 v[86:87], v[80:81], v[90:91], v[216:217] op_sel_hi:[1,0,1]
	v_pk_fma_f32 v[80:81], v[78:79], v[90:91], v[214:215] op_sel_hi:[1,0,1]
	v_cvt_pk_bf16_f32 v78, v82, v83
	v_add_co_u32_e32 v82, vcc, s2, v4
	v_pk_fma_f32 v[84:85], v[84:85], v[90:91], v[212:213] op_sel_hi:[1,0,1]
	s_nop 0
	v_addc_co_u32_e32 v83, vcc, 0, v5, vcc
	v_cvt_pk_bf16_f32 v79, v84, v85
	v_cvt_pk_bf16_f32 v80, v80, v81
	v_cvt_pk_bf16_f32 v81, v86, v87
	global_store_dwordx4 v[82:83], v[78:81], off
	v_pk_fma_f32 v[76:77], v[76:77], v[90:91], v[220:221] op_sel_hi:[1,0,1]
	v_pk_fma_f32 v[74:75], v[74:75], v[90:91], v[218:219] op_sel_hi:[1,0,1]
	v_pk_fma_f32 v[78:79], v[72:73], v[90:91], v[224:225] op_sel_hi:[1,0,1]
	v_pk_fma_f32 v[72:73], v[70:71], v[90:91], v[222:223] op_sel_hi:[1,0,1]
	v_cvt_pk_bf16_f32 v70, v74, v75
	v_cvt_pk_bf16_f32 v71, v76, v77
	v_lshl_add_u64 v[74:75], v[154:155], 0, s[24:25]
	v_cvt_pk_bf16_f32 v72, v72, v73
	v_cvt_pk_bf16_f32 v73, v78, v79
	global_store_dwordx4 v[82:83], v[70:73], off offset:256
	v_add_co_u32_e32 v78, vcc, s74, v154
	v_lshl_add_u64 v[82:83], v[154:155], 0, s[26:27]
	s_nop 0
	v_addc_co_u32_e32 v79, vcc, 0, v155, vcc
	global_load_dwordx4 v[70:73], v[78:79], off
	s_nop 0
	global_load_dwordx4 v[74:77], v[74:75], off offset:16
	s_nop 0
	global_load_dwordx4 v[78:81], v[78:79], off offset:512
	v_add_co_u32_e32 v94, vcc, s75, v154
	global_load_dwordx4 v[82:85], v[82:83], off offset:16
	s_nop 0
	v_addc_co_u32_e32 v95, vcc, 0, v155, vcc
	global_load_dwordx4 v[86:89], v[94:95], off
	v_lshl_add_u64 v[90:91], v[154:155], 0, s[28:29]
	global_load_dwordx4 v[90:93], v[90:91], off offset:16
	s_nop 0
	global_load_dwordx4 v[94:97], v[94:95], off offset:512
	v_add_co_u32_e32 v110, vcc, s76, v154
	global_load_dwordx4 v[98:101], v[98:99], off offset:16
	s_nop 0
	v_addc_co_u32_e32 v111, vcc, 0, v155, vcc
	global_load_dwordx4 v[102:105], v[110:111], off
	s_nop 0
	global_load_dwordx4 v[106:109], v[106:107], off offset:16
	s_nop 0
	global_load_dwordx4 v[110:113], v[110:111], off offset:512
	v_add_co_u32_e32 v126, vcc, s77, v154
	global_load_dwordx4 v[114:117], v[114:115], off offset:16
	s_nop 0
	v_addc_co_u32_e32 v127, vcc, 0, v155, vcc
	global_load_dwordx4 v[118:121], v[126:127], off
	s_nop 0
	global_load_dwordx4 v[122:125], v[122:123], off offset:16
	ds_read_b32 v154, v3 offset:1028
	global_load_dwordx4 v[126:129], v[126:127], off offset:512
	s_nop 0
	global_load_dwordx4 v[130:133], v[130:131], off offset:16
	v_add_co_u32_e32 v156, vcc, s78, v4
	s_mov_b64 s[2:3], -1
	s_nop 0
	v_addc_co_u32_e32 v157, vcc, 0, v5, vcc
	s_waitcnt vmcnt(15) lgkmcnt(0)
	v_pk_fma_f32 v[68:69], v[68:69], v[154:155], v[72:73] op_sel_hi:[1,0,1]
	v_pk_fma_f32 v[66:67], v[66:67], v[154:155], v[70:71] op_sel_hi:[1,0,1]
	s_waitcnt vmcnt(14)
	v_pk_fma_f32 v[64:65], v[64:65], v[154:155], v[76:77] op_sel_hi:[1,0,1]
	v_pk_fma_f32 v[62:63], v[62:63], v[154:155], v[74:75] op_sel_hi:[1,0,1]
	s_waitcnt vmcnt(13)
; __device__ __forceinline__ float bflo(unsigned w) { return __uint_as_float(w << 16); }
; __device__ __forceinline__ float bfhi(unsigned w) { return __uint_as_float(w & 0xffff0000u); }
; #define PG8_BAR __builtin_amdgcn_s_barrier()
; template <class Epi, class Sched, bool ALIGN_EPI = false, bool SP2 = false>
; __device__ __forceinline__ void gemm_phase(PG8_LAS unsigned char* lds, const Gemm g, const Sched& S, const Epi& E) {
;     ...
;         if constexpr (!Epi::AFTER_DRAIN) { E(acc, cur, ui, wr, wc, fr, fq); S.done(cur); }
;         if (!has_next) break;
; #pragma unroll
;         for (int a = 0; a < 2; ++a)
; #pragma unroll
;             for (int b = 0; b < 2; ++b)
; #pragma unroll
;                 for (int m = 0; m < 4; ++m)
; #pragma unroll
;                     for (int n = 0; n < 2; ++n) acc[a][b][m][n] = (f32x4){0.f, 0.f, 0.f, 0.f};
;         cur = nxt; cA = nA; cB = nB; ++ui;
;         if constexpr (ALIGN_EPI) { if (wr == 1) PG8_BAR; }
;     }
;     __device__ __forceinline__ void operator()(const pg8::f32x4 (&acc)[2][2][4][2], const pg8::Unit& u, int ui, int wr, int wc, int fr, int fq) const {
;     ...
;             for (int m = 0; m < 4; ++m) { const size_t ro = off0 + (size_t)(ai * 128 + m * 16) * D;
; #pragma unroll
;                 for (int bj = 0; bj < 2; ++bj) {
;                     if (l == 0) { x[m][bj][0] = *(const pg8::f32x4*)(xin_p + ro + bj * 128); x[m][bj][1] = *(const pg8::f32x4*)(xin_p + ro + bj * 128 + 4); }
;                     else { const u32x4 w = *(const u32x4*)(xb + ro + bj * 128);
;                            x[m][bj][0] = (pg8::f32x4){bflo(w.x), bfhi(w.x), bflo(w.y), bfhi(w.y)}; x[m][bj][1] = (pg8::f32x4){bflo(w.z), bfhi(w.z), bflo(w.w), bfhi(w.w)}; } } }
; #pragma unroll
;             for (int m = 0; m < 4; ++m) { const size_t ro = off0 + (size_t)(ai * 128 + m * 16) * D; const float rB = tb[(ai * 128 + m * 16) * 2];
; #pragma unroll
;                 for (int bj = 0; bj < 2; ++bj) {
;                     const pg8::f32x4 y0 = x[m][bj][0] + acc[ai][bj][m][0] * rB, y1 = x[m][bj][1] + acc[ai][bj][m][1] * rB;
;                     u32x4 o; o.x = pg8::cvt_pk_bf16(y0[0], y0[1]); o.y = pg8::cvt_pk_bf16(y0[2], y0[3]); o.z = pg8::cvt_pk_bf16(y1[0], y1[1]); o.w = pg8::cvt_pk_bf16(y1[2], y1[3]);
;                     *(u32x4*)(xb + ro + bj * 128) = o; } }
	v_pk_fma_f32 v[58:59], v[58:59], v[154:155], v[78:79] op_sel_hi:[1,0,1]
	s_waitcnt vmcnt(12)
	v_pk_fma_f32 v[70:71], v[56:57], v[154:155], v[84:85] op_sel_hi:[1,0,1]
	v_pk_fma_f32 v[72:73], v[54:55], v[154:155], v[82:83] op_sel_hi:[1,0,1]
	v_cvt_pk_bf16_f32 v54, v66, v67
	v_cvt_pk_bf16_f32 v55, v68, v69
	v_cvt_pk_bf16_f32 v56, v62, v63
	v_cvt_pk_bf16_f32 v57, v64, v65
	v_pk_fma_f32 v[60:61], v[60:61], v[154:155], v[80:81] op_sel_hi:[1,0,1]
	global_store_dwordx4 v[156:157], v[54:57], off
	s_nop 1
	v_cvt_pk_bf16_f32 v54, v58, v59
	v_cvt_pk_bf16_f32 v55, v60, v61
	v_cvt_pk_bf16_f32 v56, v72, v73
	v_cvt_pk_bf16_f32 v57, v70, v71
	ds_read_b32 v58, v3 offset:1156
	global_store_dwordx4 v[156:157], v[54:57], off offset:256
	s_waitcnt vmcnt(13) lgkmcnt(0)
	v_pk_fma_f32 v[50:51], v[50:51], v[58:59], v[86:87] op_sel_hi:[1,0,1]
	s_waitcnt vmcnt(12)
	v_pk_fma_f32 v[54:55], v[48:49], v[58:59], v[92:93] op_sel_hi:[1,0,1]
	v_pk_fma_f32 v[48:49], v[46:47], v[58:59], v[90:91] op_sel_hi:[1,0,1]
	v_cvt_pk_bf16_f32 v46, v50, v51
	v_add_co_u32_e32 v50, vcc, s79, v4
	v_pk_fma_f32 v[52:53], v[52:53], v[58:59], v[88:89] op_sel_hi:[1,0,1]
	s_nop 0
	v_addc_co_u32_e32 v51, vcc, 0, v5, vcc
	v_cvt_pk_bf16_f32 v47, v52, v53
	v_cvt_pk_bf16_f32 v48, v48, v49
	v_cvt_pk_bf16_f32 v49, v54, v55
	global_store_dwordx4 v[50:51], v[46:49], off
	s_waitcnt vmcnt(12)
	v_pk_fma_f32 v[42:43], v[42:43], v[58:59], v[94:95] op_sel_hi:[1,0,1]
	v_pk_fma_f32 v[44:45], v[44:45], v[58:59], v[96:97] op_sel_hi:[1,0,1]
	s_waitcnt vmcnt(11)
	v_pk_fma_f32 v[46:47], v[40:41], v[58:59], v[100:101] op_sel_hi:[1,0,1]
	v_pk_fma_f32 v[40:41], v[38:39], v[58:59], v[98:99] op_sel_hi:[1,0,1]
	v_cvt_pk_bf16_f32 v38, v42, v43
	v_cvt_pk_bf16_f32 v39, v44, v45
	s_nop 0
	v_cvt_pk_bf16_f32 v40, v40, v41
	v_cvt_pk_bf16_f32 v41, v46, v47
	ds_read_b32 v42, v3 offset:1284
	global_store_dwordx4 v[50:51], v[38:41], off offset:256
	s_waitcnt vmcnt(11) lgkmcnt(0)
	v_pk_fma_f32 v[34:35], v[34:35], v[42:43], v[102:103] op_sel_hi:[1,0,1]
	s_waitcnt vmcnt(10)
	v_pk_fma_f32 v[38:39], v[32:33], v[42:43], v[108:109] op_sel_hi:[1,0,1]
	v_pk_fma_f32 v[32:33], v[30:31], v[42:43], v[106:107] op_sel_hi:[1,0,1]
	v_cvt_pk_bf16_f32 v30, v34, v35
	v_add_co_u32_e32 v34, vcc, s80, v4
	v_pk_fma_f32 v[36:37], v[36:37], v[42:43], v[104:105] op_sel_hi:[1,0,1]
	s_nop 0
	v_addc_co_u32_e32 v35, vcc, 0, v5, vcc
	v_cvt_pk_bf16_f32 v31, v36, v37
	v_cvt_pk_bf16_f32 v32, v32, v33
	v_cvt_pk_bf16_f32 v33, v38, v39
	global_store_dwordx4 v[34:35], v[30:33], off
	s_waitcnt vmcnt(10)
	v_pk_fma_f32 v[26:27], v[26:27], v[42:43], v[110:111] op_sel_hi:[1,0,1]
	v_pk_fma_f32 v[28:29], v[28:29], v[42:43], v[112:113] op_sel_hi:[1,0,1]
	s_waitcnt vmcnt(9)
	v_pk_fma_f32 v[30:31], v[24:25], v[42:43], v[116:117] op_sel_hi:[1,0,1]
	v_pk_fma_f32 v[24:25], v[22:23], v[42:43], v[114:115] op_sel_hi:[1,0,1]
	v_cvt_pk_bf16_f32 v22, v26, v27
	v_cvt_pk_bf16_f32 v23, v28, v29
	s_nop 0
	v_cvt_pk_bf16_f32 v24, v24, v25
	v_cvt_pk_bf16_f32 v25, v30, v31
	ds_read_b32 v26, v3 offset:1412
	global_store_dwordx4 v[34:35], v[22:25], off offset:256
	s_waitcnt vmcnt(9) lgkmcnt(0)
	v_pk_fma_f32 v[18:19], v[18:19], v[26:27], v[118:119] op_sel_hi:[1,0,1]
	s_waitcnt vmcnt(8)
	v_pk_fma_f32 v[22:23], v[16:17], v[26:27], v[124:125] op_sel_hi:[1,0,1]
	v_pk_fma_f32 v[16:17], v[14:15], v[26:27], v[122:123] op_sel_hi:[1,0,1]
	v_cvt_pk_bf16_f32 v14, v18, v19
	v_add_co_u32_e32 v18, vcc, s81, v4
	s_waitcnt vmcnt(6)
	v_pk_fma_f32 v[6:7], v[6:7], v[26:27], v[130:131] op_sel_hi:[1,0,1]
	v_addc_co_u32_e32 v19, vcc, 0, v5, vcc
	v_pk_fma_f32 v[4:5], v[10:11], v[26:27], v[126:127] op_sel_hi:[1,0,1]
	v_pk_fma_f32 v[20:21], v[20:21], v[26:27], v[120:121] op_sel_hi:[1,0,1]
	v_pk_fma_f32 v[12:13], v[12:13], v[26:27], v[128:129] op_sel_hi:[1,0,1]
	v_cvt_pk_bf16_f32 v15, v20, v21
	v_cvt_pk_bf16_f32 v16, v16, v17
	v_cvt_pk_bf16_f32 v17, v22, v23
	global_store_dwordx4 v[18:19], v[14:17], off
	v_pk_fma_f32 v[8:9], v[8:9], v[26:27], v[132:133] op_sel_hi:[1,0,1]
	v_cvt_pk_bf16_f32 v4, v4, v5
	v_cvt_pk_bf16_f32 v5, v12, v13
	v_cvt_pk_bf16_f32 v6, v6, v7
	s_andn2_b64 vcc, exec, s[6:7]
	v_cvt_pk_bf16_f32 v7, v8, v9
	global_store_dwordx4 v[18:19], v[4:7], off offset:256
	s_cbranch_vccnz .LBB0_633
	s_andn2_b64 vcc, exec, s[14:15]
	s_cbranch_vccnz .LBB0_632
	s_barrier
	s_branch .LBB0_632

; #define PG8_STAGE(bufoff, gbase, voff) do { _Pragma("unroll") for (int _i = 0; _i < 2; ++_i) \
;         __builtin_amdgcn_global_load_lds((const unsigned*)((const char*)(gbase) + (voff)[_i]), (PG8_LAS unsigned*)(lds + (bufoff) + ldsw + _i * 8192), 16, 0, 0); } while (0)
; #define PG8_WAIT_V(n) asm volatile("s_waitcnt vmcnt(" #n ")" ::: "memory")
; #define PG8_BAR __builtin_amdgcn_s_barrier()
; template <class Epi, class Sched, bool ALIGN_EPI = false, bool SP2 = false>
; __device__ __forceinline__ void gemm_phase(PG8_LAS unsigned char* lds, const Gemm g, const Sched& S, const Epi& E) {
;     ...
;     for (int i = 0; i < 2; ++i) { int R, C; stage_rc(tid * 16 + i * 8192, R, C); const int Rb = Epi::PERM ? ((R & ~31) + perm32(R & 31)) : R;
;         voffA[i] = (unsigned)(R * K + C) * 2u; voffB[i] = (unsigned)(Rb * K + C) * 2u; }
;     const size_t kstep = (size_t)(BK * 2);
;     const size_t hstep = (size_t)HALF * K * 2;
;     const size_t tstep = 2 * hstep;
;     const unsigned ldsw = (unsigned)wid * 1024u;
;     const int aoff = lds_byte(wr * 64 + fr, fq * 8), boff = lds_byte(wc * 32 + fr, fq * 8);
;     ...
;         PG8_STAGE(PG8_SB(1, 0), cB + kstep, voffB); PG8_STAGE(PG8_SA(1, 0), cA + kstep, voffA); PG8_STAGE(PG8_SB(1, 1), cB + hstep + kstep, voffB);
;         PG8_WAIT_V(6); PG8_BAR;
;     } else {
;         PG8_STAGE(PG8_SB(0, 0), cB, voffB); PG8_STAGE(PG8_SA(0, 0), cA, voffA); PG8_STAGE(PG8_SB(0, 1), cB + hstep, voffB); PG8_STAGE(PG8_SA(0, 1), cA + hstep, voffA);
;         if (wr == 1) PG8_BAR;
;         PG8_WAIT_V(4); PG8_BAR;
;         PG8_STAGE(PG8_SB(1, 0), cB + kstep, voffB); PG8_STAGE(PG8_SA(1, 0), cA + kstep, voffA); PG8_STAGE(PG8_SB(1, 1), cB + hstep + kstep, voffB);
;         PG8_WAIT_V(6); PG8_BAR;
;     }
.LBB0_831:
	s_lshl_b32 s10, s10, 5
	s_and_b32 s24, s10, 0x60
	s_mov_b64 s[10:11], 0x80
	s_add_i32 m0, s31, 0x18000
	v_lshl_add_u64 v[8:9], v[8:9], 0, s[10:11]
	s_lshl_b32 s21, s20, 13
	s_lshl_b32 s25, s24, 7
	s_waitcnt vmcnt(2)
	s_barrier
	global_load_lds_dwordx4 v[8:9], off
	v_lshl_add_u64 v[6:7], v[6:7], 0, s[10:11]
	s_add_i32 m0, s31, 0x1a000
	s_add_i32 s48, s31, 0x8000
	s_add_i32 s49, s31, 0xa000
	global_load_lds_dwordx4 v[6:7], off
	v_lshl_add_u64 v[2:3], v[2:3], 0, s[10:11]
	s_mov_b32 m0, s48
	s_add_u32 s22, s2, 0x40080
	global_load_lds_dwordx4 v[2:3], off
	v_lshl_add_u64 v[2:3], v[4:5], 0, s[10:11]
	s_mov_b32 m0, s49
	s_addc_u32 s23, s3, 0
	global_load_lds_dwordx4 v[2:3], off
	s_add_i32 m0, s31, 0x1c000
	v_lshl_add_u64 v[2:3], s[22:23], 0, v[132:133]
	global_load_lds_dwordx4 v[2:3], off
	v_lshl_add_u64 v[2:3], s[22:23], 0, v[136:137]
	s_add_i32 m0, s31, 0x1e000
	s_cmpk_lt_u32 s5, 0x100
	global_load_lds_dwordx4 v[2:3], off
	v_lshrrev_b32_e32 v3, 1, v10
	v_and_b32_e32 v3, 24, v3
	v_and_b32_e32 v2, 15, v10
	v_lshlrev_b32_e32 v4, 1, v3
	v_lshl_or_b32 v1, s20, 6, v2
	v_lshl_or_b32 v2, v2, 6, v4
	v_lshlrev_b32_e32 v4, 2, v10
	v_and_b32_e32 v4, 32, v4
	v_bitop3_b32 v5, v2, s21, v4 bitop3:0xde
	v_bitop3_b32 v156, v2, s25, v4 bitop3:0xde
	v_lshlrev_b32_e32 v2, 14, v14
	v_and_b32_e32 v2, 0xffff8000, v2
	v_or_b32_e32 v160, s24, v3
	v_lshl_add_u32 v2, v15, 11, v2
	v_and_b32_e32 v3, 1, v14
	v_lshl_or_b32 v2, v3, 6, v2
	v_lshl_add_u32 v140, v16, 1, v2
	v_lshlrev_b32_e32 v2, 14, v11
	v_and_b32_e32 v2, 0xffff8000, v2
	s_waitcnt vmcnt(6)
	v_lshl_add_u32 v2, v12, 11, v2
	v_and_b32_e32 v3, 1, v11
	s_cselect_b64 s[20:21], -1, 0
	v_lshl_or_b32 v2, v3, 6, v2
	s_add_i32 s51, 0, 0x10000
	s_add_i32 s52, 0, 0x14000
	s_sext_i32_i8 s53, s4
	v_or_b32_e32 v157, 16, v1
	v_or_b32_e32 v158, 32, v1
	v_or_b32_e32 v159, 48, v1
	s_ashr_i32 s50, s33, 31
	v_mov_b32_e32 v141, v139
	v_lshl_add_u32 v142, v13, 1, v2
	v_mov_b32_e32 v143, v139
	v_mov_b64_e32 v[144:145], 0x1000
	v_mov_b64_e32 v[146:147], 0xfff
	v_add_u32_e32 v161, s51, v156
	v_add_u32_e32 v162, s52, v156
	v_add_u32_e32 v163, 0, v5
	s_barrier
	s_mov_b32 s62, 0
	s_branch .LBB0_834

; template <class Epi, class Sched, bool ALIGN_EPI = false, bool SP2 = false>
; __device__ __forceinline__ void gemm_phase(PG8_LAS unsigned char* lds, const Gemm g, const Sched& S, const Epi& E) {
;     ...
;         cur = nxt; cA = nA; cB = nB; ++ui;
.LBB0_833:
	s_mov_b32 s62, 1
	s_andn2_b64 vcc, exec, s[2:3]
	s_mov_b32 s53, s22
	s_mov_b32 s30, s24
	s_mov_b64 s[2:3], s[28:29]
	s_mov_b64 s[34:35], s[26:27]
	s_cbranch_vccz .LBB0_857

; __device__ __forceinline__ unsigned cvt_pk_bf16(float lo, float hi) { unsigned r; asm volatile("v_cvt_pk_bf16_f32 %0, %1, %2" : "=v"(r) : "v"(lo), "v"(hi)); return r; }
;     __device__ __forceinline__ void operator()(const pg8::f32x4 (&acc_)[2][2][4][2], const pg8::Unit& u, int, int wr, int wc, int fr, int fq) const {
;     ...
;         pg8::f32x4 acc[2][2][4][2];
; #pragma unroll
;         for (int ai = 0; ai < 2; ++ai)
; #pragma unroll
;             for (int m = 0; m < 4; ++m) { const float rs = rstd ? rstd[u.pm * 256 + ai * 128 + wr * 64 + m * 16 + fr] : 1.0f;
; #pragma unroll
;                 for (int bj = 0; bj < 2; ++bj)
; #pragma unroll
;                     for (int n = 0; n < 2; ++n) acc[ai][bj][m][n] = acc_[ai][bj][m][n] * rs; }
; #pragma unroll
;         for (int ai = 0; ai < 2; ++ai)
; #pragma unroll
;             for (int m = 0; m < 4; ++m) {
;                 const int grow = u.pm * 256 + ai * 128 + wr * 64 + m * 16 + fr;
; #pragma unroll
;                 for (int bj = 0; bj < 2; ++bj) {
;                     const int cc = cc0 + bj * 128;
;                     const pg8::f32x4 v0 = acc[ai][bj][m][0], v1 = acc[ai][bj][m][1];
;                     u32x4 w; w.x = pg8::cvt_pk_bf16(v0[0] * sc, v0[1] * sc); w.y = pg8::cvt_pk_bf16(v0[2] * sc, v0[3] * sc); w.z = pg8::cvt_pk_bf16(v1[0] * sc, v1[1] * sc); w.w = pg8::cvt_pk_bf16(v1[2] * sc, v1[3] * sc);
;                     *(u32x4*)(bbuf + (size_t)grow * D + cc) = w;
.LBB0_854:
	s_lshl_b32 s25, s30, 8
	v_add_u32_e32 v164, s25, v1
	v_ashrrev_i32_e32 v165, 31, v164
	s_lshl_b32 s63, s24, 8
	v_add_u32_e32 v244, s63, v1
	v_ashrrev_i32_e32 v245, 31, v244
	v_lshl_add_u64 v[244:245], v[244:245], 2, s[18:19]
	s_cmp_lg_u32 s62, 0
	s_cbranch_scc1 .Lrs_pipe_l1
	v_add_u32_e32 v154, 0x80, v164
	v_lshl_add_u64 v[148:149], v[164:165], 2, s[18:19]
	v_ashrrev_i32_e32 v155, 31, v154
	v_add_u32_e32 v152, 0x90, v164
	global_load_dword v138, v[148:149], off
	global_load_dword v166, v[148:149], off offset:64
	global_load_dword v168, v[148:149], off offset:128
	global_load_dword v170, v[148:149], off offset:192
	v_lshl_add_u64 v[148:149], v[154:155], 2, s[18:19]
	v_ashrrev_i32_e32 v153, 31, v152
	v_add_u32_e32 v150, 0xa0, v164
	global_load_dword v172, v[148:149], off
	v_lshl_add_u64 v[148:149], v[152:153], 2, s[18:19]
	v_ashrrev_i32_e32 v151, 31, v150
	global_load_dword v174, v[148:149], off
	v_lshl_add_u64 v[148:149], v[150:151], 2, s[18:19]
	global_load_dword v176, v[148:149], off
	v_add_u32_e32 v148, 0xb0, v164
	v_ashrrev_i32_e32 v149, 31, v148
	v_lshl_add_u64 v[178:179], v[148:149], 2, s[18:19]
	global_load_dword v178, v[178:179], off
	global_load_dword v248, v[244:245], off
	global_load_dword v249, v[244:245], off offset:64
	global_load_dword v250, v[244:245], off offset:128
	global_load_dword v251, v[244:245], off offset:192
	global_load_dword v252, v[244:245], off offset:512
	global_load_dword v253, v[244:245], off offset:576
	global_load_dword v254, v[244:245], off offset:640
	global_load_dword v255, v[244:245], off offset:704
	s_waitcnt vmcnt(0)
	s_branch .Lrs_join_l1
.Lrs_pipe_l1:
	v_add_u32_e32 v154, 0x80, v164
	v_lshl_add_u64 v[148:149], v[164:165], 2, s[18:19]
	v_ashrrev_i32_e32 v155, 31, v154
	v_add_u32_e32 v152, 0x90, v164
	v_mov_b32_e32 v138, v248
	v_mov_b32_e32 v166, v249
	v_mov_b32_e32 v168, v250
	v_mov_b32_e32 v170, v251
	v_lshl_add_u64 v[148:149], v[154:155], 2, s[18:19]
	v_ashrrev_i32_e32 v153, 31, v152
	v_add_u32_e32 v150, 0xa0, v164
	v_mov_b32_e32 v172, v252
	v_lshl_add_u64 v[148:149], v[152:153], 2, s[18:19]
	v_ashrrev_i32_e32 v151, 31, v150
	v_mov_b32_e32 v174, v253
	v_lshl_add_u64 v[148:149], v[150:151], 2, s[18:19]
	v_mov_b32_e32 v176, v254
	v_add_u32_e32 v148, 0xb0, v164
	v_ashrrev_i32_e32 v149, 31, v148
	v_lshl_add_u64 v[178:179], v[148:149], 2, s[18:19]
	v_mov_b32_e32 v178, v255
	global_load_dword v248, v[244:245], off
	global_load_dword v249, v[244:245], off offset:64
	global_load_dword v250, v[244:245], off offset:128
	global_load_dword v251, v[244:245], off offset:192
	global_load_dword v252, v[244:245], off offset:512
	global_load_dword v253, v[244:245], off offset:576
	global_load_dword v254, v[244:245], off offset:640
	global_load_dword v255, v[244:245], off offset:704
.Lrs_join_l1:
	s_lshl_b32 s30, s53, 8
	s_and_b32 s30, s30, 0x300
	v_or_b32_e32 v177, s30, v160
	s_andn2_b64 vcc, exec, s[4:5]
	v_pk_mul_f32 v[126:127], v[126:127], v[138:139] op_sel_hi:[1,0]
	v_pk_mul_f32 v[128:129], v[128:129], v[138:139] op_sel_hi:[1,0]
	v_pk_mul_f32 v[120:121], v[120:121], v[166:167] op_sel_hi:[1,0]
	v_pk_mul_f32 v[118:119], v[118:119], v[166:167] op_sel_hi:[1,0]
	v_pk_mul_f32 v[116:117], v[116:117], v[166:167] op_sel_hi:[1,0]
	v_pk_mul_f32 v[114:115], v[114:115], v[166:167] op_sel_hi:[1,0]
	v_pk_mul_f32 v[92:93], v[92:93], v[166:167] op_sel_hi:[1,0]
	v_pk_mul_f32 v[90:91], v[90:91], v[166:167] op_sel_hi:[1,0]
	v_pk_mul_f32 v[84:85], v[84:85], v[166:167] op_sel_hi:[1,0]
	v_pk_mul_f32 v[82:83], v[82:83], v[166:167] op_sel_hi:[1,0]
	v_pk_mul_f32 v[180:181], v[28:29], v[174:175] op_sel_hi:[1,0]
	v_pk_mul_f32 v[166:167], v[44:45], v[172:173] op_sel_hi:[1,0]
	v_pk_mul_f32 v[28:29], v[14:15], v[176:177] op_sel_hi:[1,0]
	v_pk_mul_f32 v[44:45], v[24:25], v[174:175] op_sel_hi:[1,0]
	v_pk_mul_f32 v[24:25], v[16:17], v[176:177] op_sel_hi:[1,0]
	v_pk_mul_f32 v[122:123], v[122:123], v[138:139] op_sel_hi:[1,0]
	v_pk_mul_f32 v[14:15], v[18:19], v[178:179] op_sel_hi:[1,0]
	v_lshlrev_b64 v[18:19], 11, v[164:165]
	v_pk_mul_f32 v[16:17], v[30:31], v[178:179] op_sel_hi:[1,0]
	v_lshl_add_u64 v[30:31], s[2:3], 0, v[18:19]
	v_mul_f32_e32 v18, s23, v126
	v_mul_f32_e32 v19, s23, v127
	v_pk_mul_f32 v[182:183], v[26:27], v[174:175] op_sel_hi:[1,0]
	v_pk_mul_f32 v[26:27], v[10:11], v[176:177] op_sel_hi:[1,0]
	v_pk_mul_f32 v[10:11], v[20:21], v[178:179] op_sel_hi:[1,0]
	v_cvt_pk_bf16_f32 v18, v18, v19
	v_mul_f32_e32 v19, s23, v128
	v_mul_f32_e32 v20, s23, v129
	v_pk_mul_f32 v[124:125], v[124:125], v[138:139] op_sel_hi:[1,0]
	v_pk_mul_f32 v[108:109], v[108:109], v[138:139] op_sel_hi:[1,0]
	v_pk_mul_f32 v[106:107], v[106:107], v[138:139] op_sel_hi:[1,0]
	v_pk_mul_f32 v[100:101], v[100:101], v[138:139] op_sel_hi:[1,0]
	v_pk_mul_f32 v[98:99], v[98:99], v[138:139] op_sel_hi:[1,0]
	v_cvt_pk_bf16_f32 v19, v19, v20
	v_mul_f32_e32 v20, s23, v122
	v_mul_f32_e32 v21, s23, v123
	v_lshlrev_b32_e32 v138, 1, v177
	v_cvt_pk_bf16_f32 v20, v20, v21
	v_mul_f32_e32 v21, s23, v124
	v_lshl_add_u64 v[30:31], v[30:31], 0, v[138:139]
	v_pk_mul_f32 v[56:57], v[56:57], v[174:175] op_sel_hi:[1,0]
	v_pk_mul_f32 v[54:55], v[54:55], v[174:175] op_sel_hi:[1,0]
	v_pk_mul_f32 v[52:53], v[52:53], v[174:175] op_sel_hi:[1,0]
	v_pk_mul_f32 v[50:51], v[50:51], v[174:175] op_sel_hi:[1,0]
	v_pk_mul_f32 v[174:175], v[22:23], v[174:175] op_sel_hi:[1,0]
	v_pk_mul_f32 v[22:23], v[12:13], v[176:177] op_sel_hi:[1,0]
	v_pk_mul_f32 v[12:13], v[32:33], v[178:179] op_sel_hi:[1,0]
	v_mul_f32_e32 v32, s23, v125
	v_cvt_pk_bf16_f32 v21, v21, v32
	global_store_dwordx4 v[30:31], v[18:21], off
	v_mul_f32_e32 v32, s23, v101
	v_pk_mul_f32 v[110:111], v[110:111], v[168:169] op_sel_hi:[1,0]
; __device__ __forceinline__ unsigned cvt_pk_bf16(float lo, float hi) { unsigned r; asm volatile("v_cvt_pk_bf16_f32 %0, %1, %2" : "=v"(r) : "v"(lo), "v"(hi)); return r; }
;     __device__ __forceinline__ void operator()(const pg8::f32x4 (&acc_)[2][2][4][2], const pg8::Unit& u, int, int wr, int wc, int fr, int fq) const {
;     ...
;         for (int ai = 0; ai < 2; ++ai)
; #pragma unroll
;             for (int m = 0; m < 4; ++m) {
;                 const int grow = u.pm * 256 + ai * 128 + wr * 64 + m * 16 + fr;
; #pragma unroll
;                 for (int bj = 0; bj < 2; ++bj) {
;                     const int cc = cc0 + bj * 128;
;                     const pg8::f32x4 v0 = acc[ai][bj][m][0], v1 = acc[ai][bj][m][1];
;                     u32x4 w; w.x = pg8::cvt_pk_bf16(v0[0] * sc, v0[1] * sc); w.y = pg8::cvt_pk_bf16(v0[2] * sc, v0[3] * sc); w.z = pg8::cvt_pk_bf16(v1[0] * sc, v1[1] * sc); w.w = pg8::cvt_pk_bf16(v1[2] * sc, v1[3] * sc);
;                     *(u32x4*)(bbuf + (size_t)grow * D + cc) = w;
	v_mul_f32_e32 v18, s23, v106
	v_mul_f32_e32 v19, s23, v107
	v_cvt_pk_bf16_f32 v18, v18, v19
	v_mul_f32_e32 v19, s23, v108
	v_mul_f32_e32 v20, s23, v109
	v_cvt_pk_bf16_f32 v19, v19, v20
	v_mul_f32_e32 v20, s23, v98
	v_mul_f32_e32 v21, s23, v99
	v_cvt_pk_bf16_f32 v20, v20, v21
	v_mul_f32_e32 v21, s23, v100
	v_cvt_pk_bf16_f32 v21, v21, v32
	global_store_dwordx4 v[30:31], v[18:21], off offset:256
	v_mul_f32_e32 v32, s23, v117
	v_pk_mul_f32 v[112:113], v[112:113], v[168:169] op_sel_hi:[1,0]
	v_add_u32_e32 v18, s25, v157
	v_ashrrev_i32_e32 v19, 31, v18
	v_lshlrev_b64 v[18:19], 11, v[18:19]
	v_lshl_add_u64 v[30:31], s[2:3], 0, v[18:19]
	v_mul_f32_e32 v18, s23, v118
	v_mul_f32_e32 v19, s23, v119
	v_cvt_pk_bf16_f32 v18, v18, v19
	v_mul_f32_e32 v19, s23, v120
	v_mul_f32_e32 v20, s23, v121
	v_cvt_pk_bf16_f32 v19, v19, v20
	v_mul_f32_e32 v20, s23, v114
	v_mul_f32_e32 v21, s23, v115
	v_cvt_pk_bf16_f32 v20, v20, v21
	v_mul_f32_e32 v21, s23, v116
	v_lshl_add_u64 v[30:31], v[30:31], 0, v[138:139]
	v_cvt_pk_bf16_f32 v21, v21, v32
	global_store_dwordx4 v[30:31], v[18:21], off
	v_mul_f32_e32 v32, s23, v85
	v_pk_mul_f32 v[102:103], v[102:103], v[168:169] op_sel_hi:[1,0]
	v_mul_f32_e32 v18, s23, v90
	v_mul_f32_e32 v19, s23, v91
	v_cvt_pk_bf16_f32 v18, v18, v19
	v_mul_f32_e32 v19, s23, v92
	v_mul_f32_e32 v20, s23, v93
	v_cvt_pk_bf16_f32 v19, v19, v20
	v_mul_f32_e32 v20, s23, v82
	v_mul_f32_e32 v21, s23, v83
	v_cvt_pk_bf16_f32 v20, v20, v21
	v_mul_f32_e32 v21, s23, v84
	v_cvt_pk_bf16_f32 v21, v21, v32
	global_store_dwordx4 v[30:31], v[18:21], off offset:256
	v_pk_mul_f32 v[104:105], v[104:105], v[168:169] op_sel_hi:[1,0]
	v_pk_mul_f32 v[78:79], v[78:79], v[168:169] op_sel_hi:[1,0]
	v_add_u32_e32 v18, s25, v158
	v_ashrrev_i32_e32 v19, 31, v18
	v_lshlrev_b64 v[18:19], 11, v[18:19]
	v_lshl_add_u64 v[30:31], s[2:3], 0, v[18:19]
	v_mul_f32_e32 v18, s23, v110
	v_mul_f32_e32 v19, s23, v111
	v_cvt_pk_bf16_f32 v18, v18, v19
	v_mul_f32_e32 v19, s23, v112
	v_mul_f32_e32 v20, s23, v113
	v_cvt_pk_bf16_f32 v19, v19, v20
	v_mul_f32_e32 v20, s23, v102
	v_mul_f32_e32 v21, s23, v103
	v_cvt_pk_bf16_f32 v20, v20, v21
	v_mul_f32_e32 v21, s23, v104
	v_lshl_add_u64 v[30:31], v[30:31], 0, v[138:139]
	v_pk_mul_f32 v[80:81], v[80:81], v[168:169] op_sel_hi:[1,0]
	v_mul_f32_e32 v32, s23, v105
	v_cvt_pk_bf16_f32 v21, v21, v32
	global_store_dwordx4 v[30:31], v[18:21], off
	v_pk_mul_f32 v[74:75], v[74:75], v[168:169] op_sel_hi:[1,0]
	v_pk_mul_f32 v[76:77], v[76:77], v[168:169] op_sel_hi:[1,0]
	v_mul_f32_e32 v18, s23, v78
	v_mul_f32_e32 v19, s23, v79
	v_cvt_pk_bf16_f32 v18, v18, v19
	v_mul_f32_e32 v19, s23, v80
	v_mul_f32_e32 v20, s23, v81
	v_cvt_pk_bf16_f32 v19, v19, v20
	v_mul_f32_e32 v20, s23, v74
	v_mul_f32_e32 v21, s23, v75
	v_cvt_pk_bf16_f32 v20, v20, v21
	v_mul_f32_e32 v21, s23, v76
	v_mul_f32_e32 v32, s23, v77
	v_cvt_pk_bf16_f32 v21, v21, v32
	global_store_dwordx4 v[30:31], v[18:21], off offset:256
	v_pk_mul_f32 v[94:95], v[94:95], v[170:171] op_sel_hi:[1,0]
	v_pk_mul_f32 v[96:97], v[96:97], v[170:171] op_sel_hi:[1,0]
	v_add_u32_e32 v18, s25, v159
	v_ashrrev_i32_e32 v19, 31, v18
	v_lshlrev_b64 v[18:19], 11, v[18:19]
	v_lshl_add_u64 v[30:31], s[2:3], 0, v[18:19]
	v_mul_f32_e32 v18, s23, v94
	v_mul_f32_e32 v19, s23, v95
	v_pk_mul_f32 v[86:87], v[86:87], v[170:171] op_sel_hi:[1,0]
	v_cvt_pk_bf16_f32 v18, v18, v19
	v_mul_f32_e32 v19, s23, v96
	v_mul_f32_e32 v20, s23, v97
	v_pk_mul_f32 v[88:89], v[88:89], v[170:171] op_sel_hi:[1,0]
	v_cvt_pk_bf16_f32 v19, v19, v20
	v_mul_f32_e32 v20, s23, v86
	v_mul_f32_e32 v21, s23, v87
	v_pk_mul_f32 v[70:71], v[70:71], v[170:171] op_sel_hi:[1,0]
	v_cvt_pk_bf16_f32 v20, v20, v21
	v_mul_f32_e32 v21, s23, v88
	v_lshl_add_u64 v[30:31], v[30:31], 0, v[138:139]
	v_pk_mul_f32 v[72:73], v[72:73], v[170:171] op_sel_hi:[1,0]
	v_mul_f32_e32 v32, s23, v89
	v_cvt_pk_bf16_f32 v21, v21, v32
	global_store_dwordx4 v[30:31], v[18:21], off
	v_pk_mul_f32 v[66:67], v[66:67], v[170:171] op_sel_hi:[1,0]
	v_pk_mul_f32 v[68:69], v[68:69], v[170:171] op_sel_hi:[1,0]
	v_mul_f32_e32 v18, s23, v70
	v_mul_f32_e32 v19, s23, v71
	v_cvt_pk_bf16_f32 v18, v18, v19
	v_mul_f32_e32 v19, s23, v72
	v_mul_f32_e32 v20, s23, v73
	v_cvt_pk_bf16_f32 v19, v19, v20
	v_mul_f32_e32 v20, s23, v66
	v_mul_f32_e32 v21, s23, v67
	v_cvt_pk_bf16_f32 v20, v20, v21
	v_mul_f32_e32 v21, s23, v68
	v_pk_mul_f32 v[62:63], v[62:63], v[172:173] op_sel_hi:[1,0]
	v_mul_f32_e32 v32, s23, v69
	v_cvt_pk_bf16_f32 v21, v21, v32
	global_store_dwordx4 v[30:31], v[18:21], off offset:256
	v_pk_mul_f32 v[64:65], v[64:65], v[172:173] op_sel_hi:[1,0]
	v_pk_mul_f32 v[58:59], v[58:59], v[172:173] op_sel_hi:[1,0]
	v_lshlrev_b64 v[18:19], 11, v[154:155]
; __device__ __forceinline__ unsigned cvt_pk_bf16(float lo, float hi) { unsigned r; asm volatile("v_cvt_pk_bf16_f32 %0, %1, %2" : "=v"(r) : "v"(lo), "v"(hi)); return r; }
; #define PG8_BAR __builtin_amdgcn_s_barrier()
; template <class Epi, class Sched, bool ALIGN_EPI = false, bool SP2 = false>
; __device__ __forceinline__ void gemm_phase(PG8_LAS unsigned char* lds, const Gemm g, const Sched& S, const Epi& E) {
;     ...
;         if constexpr (!Epi::AFTER_DRAIN) { E(acc, cur, ui, wr, wc, fr, fq); S.done(cur); }
;         if (!has_next) break;
; #pragma unroll
;         for (int a = 0; a < 2; ++a)
; #pragma unroll
;             for (int b = 0; b < 2; ++b)
; #pragma unroll
;                 for (int m = 0; m < 4; ++m)
; #pragma unroll
;                     for (int n = 0; n < 2; ++n) acc[a][b][m][n] = (f32x4){0.f, 0.f, 0.f, 0.f};
;         cur = nxt; cA = nA; cB = nB; ++ui;
;         if constexpr (ALIGN_EPI) { if (wr == 1) PG8_BAR; }
;     }
;     __device__ __forceinline__ void operator()(const pg8::f32x4 (&acc_)[2][2][4][2], const pg8::Unit& u, int, int wr, int wc, int fr, int fq) const {
;     ...
;         for (int ai = 0; ai < 2; ++ai)
; #pragma unroll
;             for (int m = 0; m < 4; ++m) {
;                 const int grow = u.pm * 256 + ai * 128 + wr * 64 + m * 16 + fr;
; #pragma unroll
;                 for (int bj = 0; bj < 2; ++bj) {
;                     const int cc = cc0 + bj * 128;
;                     const pg8::f32x4 v0 = acc[ai][bj][m][0], v1 = acc[ai][bj][m][1];
;                     u32x4 w; w.x = pg8::cvt_pk_bf16(v0[0] * sc, v0[1] * sc); w.y = pg8::cvt_pk_bf16(v0[2] * sc, v0[3] * sc); w.z = pg8::cvt_pk_bf16(v1[0] * sc, v1[1] * sc); w.w = pg8::cvt_pk_bf16(v1[2] * sc, v1[3] * sc);
;                     *(u32x4*)(bbuf + (size_t)grow * D + cc) = w;
	v_lshl_add_u64 v[30:31], s[2:3], 0, v[18:19]
	v_mul_f32_e32 v18, s23, v62
	v_mul_f32_e32 v19, s23, v63
	v_cvt_pk_bf16_f32 v18, v18, v19
	v_mul_f32_e32 v19, s23, v64
	v_mul_f32_e32 v20, s23, v65
	v_pk_mul_f32 v[60:61], v[60:61], v[172:173] op_sel_hi:[1,0]
	v_cvt_pk_bf16_f32 v19, v19, v20
	v_mul_f32_e32 v20, s23, v58
	v_mul_f32_e32 v21, s23, v59
	v_pk_mul_f32 v[168:169], v[42:43], v[172:173] op_sel_hi:[1,0]
	v_cvt_pk_bf16_f32 v20, v20, v21
	v_mul_f32_e32 v21, s23, v60
	v_lshl_add_u64 v[30:31], v[30:31], 0, v[138:139]
	v_mul_f32_e32 v32, s23, v61
	v_cvt_pk_bf16_f32 v21, v21, v32
	global_store_dwordx4 v[30:31], v[18:21], off
	v_pk_mul_f32 v[170:171], v[36:37], v[172:173] op_sel_hi:[1,0]
	v_pk_mul_f32 v[172:173], v[34:35], v[172:173] op_sel_hi:[1,0]
	v_mul_f32_e32 v18, s23, v168
	v_mul_f32_e32 v19, s23, v169
	v_cvt_pk_bf16_f32 v18, v18, v19
	v_mul_f32_e32 v19, s23, v166
	v_mul_f32_e32 v20, s23, v167
	v_cvt_pk_bf16_f32 v19, v19, v20
	v_mul_f32_e32 v20, s23, v172
	v_mul_f32_e32 v21, s23, v173
	v_cvt_pk_bf16_f32 v20, v20, v21
	v_mul_f32_e32 v21, s23, v170
	v_mul_f32_e32 v32, s23, v171
	v_cvt_pk_bf16_f32 v21, v21, v32
	global_store_dwordx4 v[30:31], v[18:21], off offset:256
	v_mul_f32_e32 v32, s23, v53
	v_pk_mul_f32 v[42:43], v[46:47], v[176:177] op_sel_hi:[1,0]
	v_lshlrev_b64 v[18:19], 11, v[152:153]
	v_lshl_add_u64 v[30:31], s[2:3], 0, v[18:19]
	v_mul_f32_e32 v18, s23, v54
	v_mul_f32_e32 v19, s23, v55
	v_cvt_pk_bf16_f32 v18, v18, v19
	v_mul_f32_e32 v19, s23, v56
	v_mul_f32_e32 v20, s23, v57
	v_cvt_pk_bf16_f32 v19, v19, v20
	v_mul_f32_e32 v20, s23, v50
	v_mul_f32_e32 v21, s23, v51
	v_cvt_pk_bf16_f32 v20, v20, v21
	v_mul_f32_e32 v21, s23, v52
	v_lshl_add_u64 v[30:31], v[30:31], 0, v[138:139]
	v_cvt_pk_bf16_f32 v21, v21, v32
	global_store_dwordx4 v[30:31], v[18:21], off
	v_mul_f32_e32 v32, s23, v45
	v_pk_mul_f32 v[36:37], v[48:49], v[176:177] op_sel_hi:[1,0]
	v_mul_f32_e32 v18, s23, v182
	v_mul_f32_e32 v19, s23, v183
	v_cvt_pk_bf16_f32 v18, v18, v19
	v_mul_f32_e32 v19, s23, v180
	v_mul_f32_e32 v20, s23, v181
	v_cvt_pk_bf16_f32 v19, v19, v20
	v_mul_f32_e32 v20, s23, v174
	v_mul_f32_e32 v21, s23, v175
	v_cvt_pk_bf16_f32 v20, v20, v21
	v_mul_f32_e32 v21, s23, v44
	v_cvt_pk_bf16_f32 v21, v21, v32
	global_store_dwordx4 v[30:31], v[18:21], off offset:256
	v_pk_mul_f32 v[38:39], v[38:39], v[176:177] op_sel_hi:[1,0]
	v_pk_mul_f32 v[34:35], v[40:41], v[176:177] op_sel_hi:[1,0]
	v_lshlrev_b64 v[18:19], 11, v[150:151]
	v_lshl_add_u64 v[30:31], s[2:3], 0, v[18:19]
	v_mul_f32_e32 v18, s23, v42
	v_mul_f32_e32 v19, s23, v43
	v_cvt_pk_bf16_f32 v18, v18, v19
	v_mul_f32_e32 v19, s23, v36
	v_mul_f32_e32 v20, s23, v37
	v_cvt_pk_bf16_f32 v19, v19, v20
	v_mul_f32_e32 v20, s23, v38
	v_mul_f32_e32 v21, s23, v39
	v_cvt_pk_bf16_f32 v20, v20, v21
	v_mul_f32_e32 v21, s23, v34
	v_lshl_add_u64 v[30:31], v[30:31], 0, v[138:139]
	v_mul_f32_e32 v32, s23, v35
	v_cvt_pk_bf16_f32 v21, v21, v32
	global_store_dwordx4 v[30:31], v[18:21], off
	v_pk_mul_f32 v[6:7], v[6:7], v[178:179] op_sel_hi:[1,0]
	v_mul_f32_e32 v16, s23, v16
	v_mul_f32_e32 v18, s23, v28
	v_mul_f32_e32 v19, s23, v29
	v_cvt_pk_bf16_f32 v18, v18, v19
	v_mul_f32_e32 v19, s23, v24
	v_mul_f32_e32 v20, s23, v25
	v_cvt_pk_bf16_f32 v19, v19, v20
	v_mul_f32_e32 v20, s23, v26
	v_mul_f32_e32 v21, s23, v27
	v_cvt_pk_bf16_f32 v20, v20, v21
	v_mul_f32_e32 v21, s23, v22
	v_mul_f32_e32 v22, s23, v23
	v_cvt_pk_bf16_f32 v21, v21, v22
	global_store_dwordx4 v[30:31], v[18:21], off offset:256
	v_mul_f32_e32 v17, s23, v17
	v_mul_f32_e32 v12, s23, v12
	v_lshlrev_b64 v[18:19], 11, v[148:149]
	v_lshl_add_u64 v[20:21], s[2:3], 0, v[18:19]
	v_mul_f32_e32 v13, s23, v13
	v_mul_f32_e32 v10, s23, v10
	v_mul_f32_e32 v11, s23, v11
	v_pk_mul_f32 v[8:9], v[8:9], v[178:179] op_sel_hi:[1,0]
	v_pk_mul_f32 v[2:3], v[2:3], v[178:179] op_sel_hi:[1,0]
	v_cvt_pk_bf16_f32 v16, v16, v17
	v_cvt_pk_bf16_f32 v17, v12, v13
	v_mul_f32_e32 v12, s23, v14
	v_mul_f32_e32 v13, s23, v15
	v_cvt_pk_bf16_f32 v18, v12, v13
	v_cvt_pk_bf16_f32 v19, v10, v11
	v_lshl_add_u64 v[10:11], v[20:21], 0, v[138:139]
	v_mul_f32_e32 v6, s23, v6
	v_mul_f32_e32 v7, s23, v7
	v_pk_mul_f32 v[4:5], v[4:5], v[178:179] op_sel_hi:[1,0]
	global_store_dwordx4 v[10:11], v[16:19], off
	v_cvt_pk_bf16_f32 v6, v6, v7
	v_mul_f32_e32 v7, s23, v8
	v_mul_f32_e32 v8, s23, v9
	v_mul_f32_e32 v2, s23, v2
	v_mul_f32_e32 v3, s23, v3
	s_mov_b64 s[2:3], -1
	v_cvt_pk_bf16_f32 v7, v7, v8
	v_cvt_pk_bf16_f32 v8, v2, v3
	v_mul_f32_e32 v2, s23, v4
	v_mul_f32_e32 v3, s23, v5
	v_cvt_pk_bf16_f32 v9, v2, v3
	global_store_dwordx4 v[10:11], v[6:9], off offset:256
	s_cbranch_vccnz .LBB0_833
	s_andn2_b64 vcc, exec, s[8:9]
	s_cbranch_vccnz .LBB0_832
	s_barrier
	s_branch .LBB0_832

; #define PG8_STAGE(bufoff, gbase, voff) do { _Pragma("unroll") for (int _i = 0; _i < 2; ++_i) \
;         __builtin_amdgcn_global_load_lds((const unsigned*)((const char*)(gbase) + (voff)[_i]), (PG8_LAS unsigned*)(lds + (bufoff) + ldsw + _i * 8192), 16, 0, 0); } while (0)
; #define PG8_WAIT_V(n) asm volatile("s_waitcnt vmcnt(" #n ")" ::: "memory")
; #define PG8_BAR __builtin_amdgcn_s_barrier()
; template <class Epi, class Sched, bool ALIGN_EPI = false, bool SP2 = false>
; __device__ __forceinline__ void gemm_phase(PG8_LAS unsigned char* lds, const Gemm g, const Sched& S, const Epi& E) {
;     ...
;     for (int i = 0; i < 2; ++i) { int R, C; stage_rc(tid * 16 + i * 8192, R, C); const int Rb = Epi::PERM ? ((R & ~31) + perm32(R & 31)) : R;
;         voffA[i] = (unsigned)(R * K + C) * 2u; voffB[i] = (unsigned)(Rb * K + C) * 2u; }
;     const size_t kstep = (size_t)(BK * 2);
;     const size_t hstep = (size_t)HALF * K * 2;
;     const size_t tstep = 2 * hstep;
;     const unsigned ldsw = (unsigned)wid * 1024u;
;     const int aoff = lds_byte(wr * 64 + fr, fq * 8), boff = lds_byte(wc * 32 + fr, fq * 8);
;     ...
;         PG8_STAGE(PG8_SB(1, 0), cB + kstep, voffB); PG8_STAGE(PG8_SA(1, 0), cA + kstep, voffA); PG8_STAGE(PG8_SB(1, 1), cB + hstep + kstep, voffB);
;         PG8_WAIT_V(6); PG8_BAR;
;     } else {
;         PG8_STAGE(PG8_SB(0, 0), cB, voffB); PG8_STAGE(PG8_SA(0, 0), cA, voffA); PG8_STAGE(PG8_SB(0, 1), cB + hstep, voffB); PG8_STAGE(PG8_SA(0, 1), cA + hstep, voffA);
;         if (wr == 1) PG8_BAR;
;         PG8_WAIT_V(4); PG8_BAR;
;         PG8_STAGE(PG8_SB(1, 0), cB + kstep, voffB); PG8_STAGE(PG8_SA(1, 0), cA + kstep, voffA); PG8_STAGE(PG8_SB(1, 1), cB + hstep + kstep, voffB);
;         PG8_WAIT_V(6); PG8_BAR;
;     }
.LBB0_1292:
	s_lshl_b32 s7, s7, 5
	s_mov_b64 s[14:15], 0x80
	s_and_b32 s7, s7, 0x60
	s_add_i32 m0, s40, 0x18000
	v_lshl_add_u64 v[10:11], v[10:11], 0, s[14:15]
	s_lshl_b32 s20, s5, 6
	s_lshl_b32 s5, s5, 13
	s_lshl_b32 s18, s7, 7
	s_waitcnt vmcnt(2)
	s_barrier
	global_load_lds_dwordx4 v[10:11], off
	v_lshl_add_u64 v[8:9], v[8:9], 0, s[14:15]
	s_add_i32 m0, s40, 0x1a000
	s_add_i32 s45, s40, 0x8000
	s_add_i32 s46, s40, 0xa000
	global_load_lds_dwordx4 v[8:9], off
	v_lshl_add_u64 v[4:5], v[4:5], 0, s[14:15]
	s_mov_b32 m0, s45
	s_add_u32 s16, s2, 0x40080
	global_load_lds_dwordx4 v[4:5], off
	v_lshl_add_u64 v[4:5], v[6:7], 0, s[14:15]
	s_mov_b32 m0, s46
	s_addc_u32 s17, s3, 0
	global_load_lds_dwordx4 v[4:5], off
	s_add_i32 m0, s40, 0x1c000
	v_lshl_add_u64 v[4:5], s[16:17], 0, v[140:141]
	global_load_lds_dwordx4 v[4:5], off
	v_lshl_add_u64 v[4:5], s[16:17], 0, v[144:145]
	s_add_i32 m0, s40, 0x1e000
	s_cmpk_lt_u32 s6, 0x100
	global_load_lds_dwordx4 v[4:5], off
	v_lshrrev_b32_e32 v5, 1, v1
	v_and_b32_e32 v5, 24, v5
	v_and_b32_e32 v4, 15, v1
	v_lshlrev_b32_e32 v6, 1, v5
	v_lshlrev_b32_e32 v1, 2, v1
	s_cselect_b64 s[16:17], -1, 0
	s_ashr_i32 s6, s20, 31
	v_or_b32_e32 v146, s20, v4
	v_lshl_or_b32 v4, v4, 6, v6
	v_and_b32_e32 v1, 32, v1
	v_mov_b32_e32 v147, s6
	v_bitop3_b32 v8, v4, s5, v1 bitop3:0xde
	v_bitop3_b32 v1, v4, s18, v1 bitop3:0xde
	v_or_b32_e32 v6, s7, v5
	v_lshlrev_b64 v[4:5], 11, v[146:147]
	v_lshl_add_u64 v[4:5], s[8:9], 0, v[4:5]
	v_lshlrev_b32_e32 v6, 1, v6
	v_mov_b32_e32 v7, v2
	v_lshl_add_u64 v[148:149], v[4:5], 0, v[6:7]
	v_lshlrev_b32_e32 v4, 14, v14
	v_and_b32_e32 v4, 0xffff8000, v4
	v_lshl_add_u32 v4, v15, 11, v4
	v_and_b32_e32 v5, 1, v14
	v_lshl_or_b32 v4, v5, 6, v4
	s_mov_b64 s[18:19], 0x40080
	v_lshl_add_u32 v4, v16, 1, v4
	v_mov_b32_e32 v5, v2
	v_lshl_add_u64 v[150:151], v[4:5], 0, s[18:19]
	v_lshlrev_b32_e32 v4, 14, v3
	v_and_b32_e32 v4, 0xffff8000, v4
	v_lshl_add_u32 v4, v12, 11, v4
	v_and_b32_e32 v3, 1, v3
	s_waitcnt vmcnt(6)
	v_lshl_or_b32 v3, v3, 6, v4
	s_sext_i32_i8 s58, s4
	s_movk_i32 s4, 0x100
	v_lshl_add_u32 v4, v13, 1, v3
	s_mov_b32 s47, 0x18000
	s_mov_b32 s48, 0x8000
	v_cmp_gt_u32_e64 s[4:5], s4, v0
	s_ashr_i32 s49, s33, 31
	v_lshl_add_u64 v[152:153], v[4:5], 0, s[18:19]
	v_mov_b32_e32 v147, 0x358637bd
	s_mov_b32 s50, 0xf800000
	v_mov_b32_e32 v164, 0x260
	s_add_i32 s51, 0, 0x10000
	s_add_i32 s52, 0, 0x14000
	v_add_u32_e32 v165, 0, v8
	s_mov_b32 s53, 0x40000
	s_mov_b32 s54, 0x48000
	s_mov_b32 s55, 0x50000
	s_mov_b32 s56, 0x58000
	v_mov_b64_e32 v[154:155], 0x400
	v_mov_b64_e32 v[156:157], 0x3ff
	s_barrier
	s_mov_b32 s93, 0
	s_branch .LBB0_1295

; #define LAS __attribute__((address_space(3)))
;     __device__ __forceinline__ void begin(const pg8::Unit& u, int ui) const {
;         const int tid = threadIdx.x;
;         if (tid < 256) {
;             const float* sq = ssq + (size_t)(u.pm * 256 + tid) * 16;
;             const pg8::f32x4 a0 = *(const pg8::f32x4*)sq, a1 = *(const pg8::f32x4*)(sq + 4), b0 = *(const pg8::f32x4*)(sq + 8), b1 = *(const pg8::f32x4*)(sq + 12);
;             const float sa = ((a0[0] + a0[1]) + (a0[2] + a0[3])) + ((a1[0] + a1[1]) + (a1[2] + a1[3]));
;             const float sb = ((b0[0] + b0[1]) + (b0[2] + b0[3])) + ((b1[0] + b1[1]) + (b1[2] + b1[3]));
;             const float rA = 1.0f / sqrtf(sa * (1.0f / W) + EPS), rB = 1.0f / sqrtf(sb * (1.0f / W) + EPS);
;             LAS float* t = tab + ((ui & 1) * 256 + tid) * 2; t[0] = rA / rB; t[1] = rB;
;         }
.LBB0_1294:
	s_mov_b32 s93, 1
	s_andn2_b64 vcc, exec, s[2:3]
	s_mov_b32 s58, s18
	s_mov_b32 s24, s20
	s_mov_b64 s[2:3], s[22:23]
	s_mov_b64 s[26:27], s[8:9]
	s_mov_b32 s28, s57
	s_cbranch_vccz .LBB0_1312
.LBB0_1295:
	s_and_saveexec_b64 s[22:23], s[4:5]
	s_cbranch_execz .LBB0_1297
	v_lshl_or_b32 v4, s24, 8, v0
	v_ashrrev_i32_e32 v5, 31, v4
	v_lshlrev_b64 v[4:5], 6, v[4:5]
	v_lshl_add_u64 v[16:17], s[10:11], 0, v[4:5]
	s_cmp_lg_u32 s93, 0
	s_cbranch_scc1 .Lob_pipe_l1
	global_load_dwordx4 v[238:241], v[16:17], off
	global_load_dwordx4 v[244:247], v[16:17], off offset:16
	global_load_dwordx4 v[248:251], v[16:17], off offset:32
	global_load_dwordx4 v[252:255], v[16:17], off offset:48
	s_waitcnt vmcnt(0)
.Lob_pipe_l1:
	s_lshl_b32 s6, s28, 8
	s_and_b32 s6, s6, 0x100
	v_or_b32_e32 v3, s6, v0
	v_lshl_add_u32 v3, v3, 3, 0
	v_add_u32_e32 v3, 0x20400, v3
	v_add_f32_e32 v4, v238, v239
	v_add_f32_e32 v5, v240, v241
	v_add_f32_e32 v6, v244, v245
	v_add_f32_e32 v7, v246, v247
	v_add_f32_e32 v8, v248, v249
	v_add_f32_e32 v9, v250, v251
	v_add_f32_e32 v10, v252, v253
	v_add_f32_e32 v11, v254, v255
	v_add_f32_e32 v4, v4, v5
	v_add_f32_e32 v5, v6, v7
	v_add_f32_e32 v6, v8, v9
	v_add_f32_e32 v7, v10, v11
	v_add_f32_e32 v4, v4, v5
	v_add_f32_e32 v5, v6, v7
	v_fmamk_f32 v4, v4, 0x3b000000, v147
	v_fmamk_f32 v5, v5, 0x3b000000, v147
	v_mul_f32_e32 v6, 0x4f800000, v4
	v_cmp_gt_f32_e32 vcc, s50, v4
	v_mul_f32_e32 v7, 0x4f800000, v5
	v_cmp_gt_f32_e64 s[6:7], s50, v5
	v_cndmask_b32_e32 v4, v4, v6, vcc
	v_sqrt_f32_e32 v6, v4
	v_cndmask_b32_e64 v5, v5, v7, s[6:7]
	v_sqrt_f32_e32 v7, v5
	v_add_u32_e32 v8, -1, v6
	v_fma_f32 v12, -v8, v6, v4
	v_add_u32_e32 v10, -1, v7
	v_add_u32_e32 v9, 1, v6
	v_fma_f32 v14, -v10, v7, v5
	v_cmp_ge_f32_e64 s[8:9], 0, v12
	v_add_u32_e32 v11, 1, v7
	v_fma_f32 v13, -v9, v6, v4
	v_cndmask_b32_e64 v6, v6, v8, s[8:9]
	v_cmp_ge_f32_e64 s[8:9], 0, v14
	v_fma_f32 v15, -v11, v7, v5
	s_nop 0
	v_cndmask_b32_e64 v7, v7, v10, s[8:9]
	v_cmp_lt_f32_e64 s[8:9], 0, v13
	s_nop 1
	v_cndmask_b32_e64 v6, v6, v9, s[8:9]
	v_cmp_lt_f32_e64 s[8:9], 0, v15
	v_mul_f32_e32 v8, 0x37800000, v6
	v_cndmask_b32_e32 v6, v6, v8, vcc
	v_cndmask_b32_e64 v7, v7, v11, s[8:9]
	v_mul_f32_e32 v9, 0x37800000, v7
	v_cmp_class_f32_e32 vcc, v4, v164
	v_cndmask_b32_e64 v7, v7, v9, s[6:7]
	s_nop 0
	v_cndmask_b32_e32 v4, v6, v4, vcc
	v_cmp_class_f32_e32 vcc, v5, v164
	v_div_scale_f32 v6, s[6:7], v4, v4, 1.0
	s_nop 0
	v_cndmask_b32_e32 v5, v7, v5, vcc
	v_div_scale_f32 v8, s[6:7], v5, v5, 1.0
	v_rcp_f32_e32 v9, v6
	v_rcp_f32_e32 v10, v8
	v_div_scale_f32 v7, vcc, 1.0, v4, 1.0
	v_fma_f32 v12, -v6, v9, 1.0
	v_fma_f32 v13, -v8, v10, 1.0
	v_fmac_f32_e32 v9, v12, v9
	v_div_scale_f32 v11, s[6:7], 1.0, v5, 1.0
	v_fmac_f32_e32 v10, v13, v10
	v_mul_f32_e32 v12, v7, v9
	v_mul_f32_e32 v13, v11, v10
	v_fma_f32 v14, -v6, v12, v7
	v_fma_f32 v15, -v8, v13, v11
	v_fmac_f32_e32 v12, v14, v9
	v_fmac_f32_e32 v13, v15, v10
	v_fma_f32 v6, -v6, v12, v7
	v_fma_f32 v7, -v8, v13, v11
	v_div_fmas_f32 v6, v6, v9, v12
	s_mov_b64 vcc, s[6:7]
	v_div_fixup_f32 v4, v6, v4, 1.0
	v_div_fmas_f32 v6, v7, v10, v13
	v_div_fixup_f32 v5, v6, v5, 1.0
	v_div_scale_f32 v6, s[6:7], v5, v5, v4
	v_rcp_f32_e32 v7, v6
	v_div_scale_f32 v8, vcc, v4, v5, v4
	v_fma_f32 v9, -v6, v7, 1.0
	v_fmac_f32_e32 v7, v9, v7
	v_mul_f32_e32 v9, v8, v7
	v_fma_f32 v10, -v6, v9, v8
	v_fmac_f32_e32 v9, v10, v7
	v_fma_f32 v6, -v6, v9, v8
	v_div_fmas_f32 v6, v6, v7, v9
	v_div_fixup_f32 v4, v6, v5, v4
	ds_write_b64 v3, v[4:5]

; #define LAS __attribute__((address_space(3)))
; __device__ __forceinline__ float bflo(unsigned w) { return __uint_as_float(w << 16); }
; __device__ __forceinline__ float bfhi(unsigned w) { return __uint_as_float(w & 0xffff0000u); }
; __device__ __forceinline__ unsigned cvt_pk_bf16(float lo, float hi) { unsigned r; asm volatile("v_cvt_pk_bf16_f32 %0, %1, %2" : "=v"(r) : "v"(lo), "v"(hi)); return r; }
;     __device__ __forceinline__ void operator()(const pg8::f32x4 (&acc)[2][2][4][2], const pg8::Unit& u, int ui, int wr, int wc, int fr, int fq) const {
;         const size_t off0 = ((size_t)u.pm * 256 + wr * 64 + fr) * D + u.pn * 256 + wc * 32 + 8 * fq;
;         const LAS float* tb = tab + ((ui & 1) * 256 + wr * 64 + fr) * 2 + 1;
;         bf16* xb = (bf16*)xp;
; #pragma unroll
;         for (int ai = 0; ai < 2; ++ai) {
;             pg8::f32x4 x[4][2][2];
; #pragma unroll
;             for (int m = 0; m < 4; ++m) { const size_t ro = off0 + (size_t)(ai * 128 + m * 16) * D;
; #pragma unroll
;                 for (int bj = 0; bj < 2; ++bj) {
;                     if (l == 0) { x[m][bj][0] = *(const pg8::f32x4*)(xin_p + ro + bj * 128); x[m][bj][1] = *(const pg8::f32x4*)(xin_p + ro + bj * 128 + 4); }
;                     else { const u32x4 w = *(const u32x4*)(xb + ro + bj * 128);
;                            x[m][bj][0] = (pg8::f32x4){bflo(w.x), bfhi(w.x), bflo(w.y), bfhi(w.y)}; x[m][bj][1] = (pg8::f32x4){bflo(w.z), bfhi(w.z), bflo(w.w), bfhi(w.w)}; } } }
; #pragma unroll
;             for (int m = 0; m < 4; ++m) { const size_t ro = off0 + (size_t)(ai * 128 + m * 16) * D; const float rB = tb[(ai * 128 + m * 16) * 2];
; #pragma unroll
;                 for (int bj = 0; bj < 2; ++bj) {
;                     const pg8::f32x4 y0 = x[m][bj][0] + acc[ai][bj][m][0] * rB, y1 = x[m][bj][1] + acc[ai][bj][m][1] * rB;
;                     u32x4 o; o.x = pg8::cvt_pk_bf16(y0[0], y0[1]); o.y = pg8::cvt_pk_bf16(y0[2], y0[3]); o.z = pg8::cvt_pk_bf16(y1[0], y1[1]); o.w = pg8::cvt_pk_bf16(y1[2], y1[3]);
;                     *(u32x4*)(xb + ro + bj * 128) = o; } }
.LBB0_1309:
	s_and_saveexec_b64 s[94:95], s[4:5]
	v_lshl_or_b32 v234, s20, 8, v0
	v_ashrrev_i32_e32 v235, 31, v234
	v_lshlrev_b64 v[234:235], 6, v[234:235]
	v_lshl_add_u64 v[234:235], s[10:11], 0, v[234:235]
	global_load_dwordx4 v[238:241], v[234:235], off
	global_load_dwordx4 v[244:247], v[234:235], off offset:16
	global_load_dwordx4 v[248:251], v[234:235], off offset:32
	global_load_dwordx4 v[252:255], v[234:235], off offset:48
	s_mov_b64 exec, s[94:95]
	s_nop 1
	s_lshl_b32 s2, s58, 8
	s_ashr_i32 s25, s24, 31
	s_ashr_i32 s3, s2, 31
	v_lshl_add_u64 v[4:5], s[2:3], 1, v[148:149]
	s_lshl_b64 s[2:3], s[24:25], 19
	v_lshl_add_u64 v[4:5], v[4:5], 0, s[2:3]
	global_load_dwordx4 v[168:171], v[4:5], off
	global_load_dwordx4 v[172:175], v[4:5], off offset:256
	v_add_co_u32_e32 v162, vcc, s48, v4
	s_add_i32 s2, 0, 0x20400
	s_nop 0
	v_addc_co_u32_e32 v163, vcc, 0, v5, vcc
	global_load_dwordx4 v[176:179], v[162:163], off
	global_load_dwordx4 v[180:183], v[162:163], off offset:256
	v_add_co_u32_e32 v160, vcc, s44, v4
	v_add_u32_e32 v3, s2, v166
	s_nop 0
	v_addc_co_u32_e32 v161, vcc, 0, v5, vcc
	global_load_dwordx4 v[184:187], v[160:161], off
	global_load_dwordx4 v[188:191], v[160:161], off offset:256
	v_add_co_u32_e32 v158, vcc, s47, v4
	s_mov_b64 s[2:3], -1
	s_nop 0
	v_addc_co_u32_e32 v159, vcc, 0, v5, vcc
	global_load_dwordx4 v[192:195], v[158:159], off
	global_load_dwordx4 v[134:137], v[158:159], off offset:256
	ds_read_b32 v166, v3 offset:4
	s_waitcnt vmcnt(0)
	v_lshlrev_b32_e32 v196, 16, v168
	v_and_b32_e32 v197, 0xffff0000, v168
	v_lshlrev_b32_e32 v168, 16, v169
	v_and_b32_e32 v169, 0xffff0000, v169
	v_lshlrev_b32_e32 v198, 16, v170
	v_and_b32_e32 v199, 0xffff0000, v170
	v_lshlrev_b32_e32 v170, 16, v171
	v_and_b32_e32 v171, 0xffff0000, v171
	v_lshlrev_b32_e32 v200, 16, v172
	v_and_b32_e32 v201, 0xffff0000, v172
	v_lshlrev_b32_e32 v202, 16, v174
	v_and_b32_e32 v203, 0xffff0000, v174
	v_lshlrev_b32_e32 v174, 16, v175
	v_and_b32_e32 v175, 0xffff0000, v175
	s_waitcnt lgkmcnt(0)
	v_pk_fma_f32 v[132:133], v[132:133], v[166:167], v[168:169] op_sel_hi:[1,0,1]
	v_pk_fma_f32 v[130:131], v[130:131], v[166:167], v[196:197] op_sel_hi:[1,0,1]
	v_pk_fma_f32 v[168:169], v[128:129], v[166:167], v[170:171] op_sel_hi:[1,0,1]
	v_pk_fma_f32 v[128:129], v[126:127], v[166:167], v[198:199] op_sel_hi:[1,0,1]
	v_cvt_pk_bf16_f32 v126, v130, v131
	v_cvt_pk_bf16_f32 v127, v132, v133
	v_lshlrev_b32_e32 v172, 16, v173
	v_and_b32_e32 v173, 0xffff0000, v173
	v_cvt_pk_bf16_f32 v128, v128, v129
	v_cvt_pk_bf16_f32 v129, v168, v169
	global_store_dwordx4 v[4:5], v[126:129], off
	v_pk_fma_f32 v[122:123], v[122:123], v[166:167], v[200:201] op_sel_hi:[1,0,1]
	v_pk_fma_f32 v[124:125], v[124:125], v[166:167], v[172:173] op_sel_hi:[1,0,1]
	v_pk_fma_f32 v[126:127], v[120:121], v[166:167], v[174:175] op_sel_hi:[1,0,1]
	v_pk_fma_f32 v[120:121], v[118:119], v[166:167], v[202:203] op_sel_hi:[1,0,1]
	v_cvt_pk_bf16_f32 v118, v122, v123
	v_cvt_pk_bf16_f32 v119, v124, v125
	v_lshlrev_b32_e32 v204, 16, v176
	v_cvt_pk_bf16_f32 v120, v120, v121
	v_cvt_pk_bf16_f32 v121, v126, v127
	ds_read_b32 v122, v3 offset:132
	v_and_b32_e32 v205, 0xffff0000, v176
	v_lshlrev_b32_e32 v176, 16, v177
	v_and_b32_e32 v177, 0xffff0000, v177
	v_lshlrev_b32_e32 v206, 16, v178
	v_and_b32_e32 v207, 0xffff0000, v178
	v_lshlrev_b32_e32 v178, 16, v179
	v_and_b32_e32 v179, 0xffff0000, v179
	v_lshlrev_b32_e32 v208, 16, v180
	v_and_b32_e32 v209, 0xffff0000, v180
	v_lshlrev_b32_e32 v210, 16, v182
	v_and_b32_e32 v211, 0xffff0000, v182
	v_lshlrev_b32_e32 v182, 16, v183
	v_and_b32_e32 v183, 0xffff0000, v183
	global_store_dwordx4 v[4:5], v[118:121], off offset:256
	s_waitcnt lgkmcnt(0)
	v_pk_fma_f32 v[116:117], v[116:117], v[122:123], v[176:177] op_sel_hi:[1,0,1]
	v_pk_fma_f32 v[114:115], v[114:115], v[122:123], v[204:205] op_sel_hi:[1,0,1]
	v_pk_fma_f32 v[118:119], v[112:113], v[122:123], v[178:179] op_sel_hi:[1,0,1]
	v_pk_fma_f32 v[112:113], v[110:111], v[122:123], v[206:207] op_sel_hi:[1,0,1]
	v_cvt_pk_bf16_f32 v110, v114, v115
	v_cvt_pk_bf16_f32 v111, v116, v117
	v_lshlrev_b32_e32 v180, 16, v181
	v_and_b32_e32 v181, 0xffff0000, v181
	v_cvt_pk_bf16_f32 v112, v112, v113
	v_cvt_pk_bf16_f32 v113, v118, v119
	global_store_dwordx4 v[162:163], v[110:113], off
	v_pk_fma_f32 v[106:107], v[106:107], v[122:123], v[208:209] op_sel_hi:[1,0,1]
	v_pk_fma_f32 v[108:109], v[108:109], v[122:123], v[180:181] op_sel_hi:[1,0,1]
	v_pk_fma_f32 v[110:111], v[104:105], v[122:123], v[182:183] op_sel_hi:[1,0,1]
	v_pk_fma_f32 v[104:105], v[102:103], v[122:123], v[210:211] op_sel_hi:[1,0,1]
	v_cvt_pk_bf16_f32 v102, v106, v107
	v_cvt_pk_bf16_f32 v103, v108, v109
	v_lshlrev_b32_e32 v212, 16, v184
	v_cvt_pk_bf16_f32 v104, v104, v105
	v_cvt_pk_bf16_f32 v105, v110, v111
	ds_read_b32 v106, v3 offset:260
	v_and_b32_e32 v213, 0xffff0000, v184
	v_lshlrev_b32_e32 v184, 16, v185
	v_and_b32_e32 v185, 0xffff0000, v185
	v_lshlrev_b32_e32 v214, 16, v186
	v_and_b32_e32 v215, 0xffff0000, v186
	v_lshlrev_b32_e32 v186, 16, v187
	v_and_b32_e32 v187, 0xffff0000, v187
	v_lshlrev_b32_e32 v216, 16, v188
	v_and_b32_e32 v217, 0xffff0000, v188
	v_lshlrev_b32_e32 v218, 16, v190
	v_and_b32_e32 v219, 0xffff0000, v190
	v_lshlrev_b32_e32 v190, 16, v191
	v_and_b32_e32 v191, 0xffff0000, v191
	global_store_dwordx4 v[162:163], v[102:105], off offset:256
	s_waitcnt lgkmcnt(0)
; __device__ __forceinline__ float bflo(unsigned w) { return __uint_as_float(w << 16); }
; __device__ __forceinline__ float bfhi(unsigned w) { return __uint_as_float(w & 0xffff0000u); }
; __device__ __forceinline__ unsigned cvt_pk_bf16(float lo, float hi) { unsigned r; asm volatile("v_cvt_pk_bf16_f32 %0, %1, %2" : "=v"(r) : "v"(lo), "v"(hi)); return r; }
;     __device__ __forceinline__ void operator()(const pg8::f32x4 (&acc)[2][2][4][2], const pg8::Unit& u, int ui, int wr, int wc, int fr, int fq) const {
;     ...
;             for (int m = 0; m < 4; ++m) { const size_t ro = off0 + (size_t)(ai * 128 + m * 16) * D;
; #pragma unroll
;                 for (int bj = 0; bj < 2; ++bj) {
;                     if (l == 0) { x[m][bj][0] = *(const pg8::f32x4*)(xin_p + ro + bj * 128); x[m][bj][1] = *(const pg8::f32x4*)(xin_p + ro + bj * 128 + 4); }
;                     else { const u32x4 w = *(const u32x4*)(xb + ro + bj * 128);
;                            x[m][bj][0] = (pg8::f32x4){bflo(w.x), bfhi(w.x), bflo(w.y), bfhi(w.y)}; x[m][bj][1] = (pg8::f32x4){bflo(w.z), bfhi(w.z), bflo(w.w), bfhi(w.w)}; } } }
; #pragma unroll
;             for (int m = 0; m < 4; ++m) { const size_t ro = off0 + (size_t)(ai * 128 + m * 16) * D; const float rB = tb[(ai * 128 + m * 16) * 2];
; #pragma unroll
;                 for (int bj = 0; bj < 2; ++bj) {
;                     const pg8::f32x4 y0 = x[m][bj][0] + acc[ai][bj][m][0] * rB, y1 = x[m][bj][1] + acc[ai][bj][m][1] * rB;
;                     u32x4 o; o.x = pg8::cvt_pk_bf16(y0[0], y0[1]); o.y = pg8::cvt_pk_bf16(y0[2], y0[3]); o.z = pg8::cvt_pk_bf16(y1[0], y1[1]); o.w = pg8::cvt_pk_bf16(y1[2], y1[3]);
;                     *(u32x4*)(xb + ro + bj * 128) = o; } }
	v_pk_fma_f32 v[100:101], v[100:101], v[106:107], v[184:185] op_sel_hi:[1,0,1]
	v_pk_fma_f32 v[98:99], v[98:99], v[106:107], v[212:213] op_sel_hi:[1,0,1]
	v_pk_fma_f32 v[102:103], v[96:97], v[106:107], v[186:187] op_sel_hi:[1,0,1]
	v_pk_fma_f32 v[96:97], v[94:95], v[106:107], v[214:215] op_sel_hi:[1,0,1]
	v_cvt_pk_bf16_f32 v94, v98, v99
	v_cvt_pk_bf16_f32 v95, v100, v101
	v_lshlrev_b32_e32 v188, 16, v189
	v_and_b32_e32 v189, 0xffff0000, v189
	v_cvt_pk_bf16_f32 v96, v96, v97
	v_cvt_pk_bf16_f32 v97, v102, v103
	global_store_dwordx4 v[160:161], v[94:97], off
	v_pk_fma_f32 v[90:91], v[90:91], v[106:107], v[216:217] op_sel_hi:[1,0,1]
	v_pk_fma_f32 v[92:93], v[92:93], v[106:107], v[188:189] op_sel_hi:[1,0,1]
	v_pk_fma_f32 v[94:95], v[88:89], v[106:107], v[190:191] op_sel_hi:[1,0,1]
	v_pk_fma_f32 v[88:89], v[86:87], v[106:107], v[218:219] op_sel_hi:[1,0,1]
	v_cvt_pk_bf16_f32 v86, v90, v91
	v_cvt_pk_bf16_f32 v87, v92, v93
	v_lshlrev_b32_e32 v220, 16, v192
	v_cvt_pk_bf16_f32 v88, v88, v89
	v_cvt_pk_bf16_f32 v89, v94, v95
	ds_read_b32 v90, v3 offset:388
	v_and_b32_e32 v221, 0xffff0000, v192
	v_lshlrev_b32_e32 v192, 16, v193
	v_and_b32_e32 v193, 0xffff0000, v193
	v_lshlrev_b32_e32 v222, 16, v194
	v_and_b32_e32 v223, 0xffff0000, v194
	v_lshlrev_b32_e32 v194, 16, v195
	v_and_b32_e32 v195, 0xffff0000, v195
	v_lshlrev_b32_e32 v110, 16, v136
	v_and_b32_e32 v111, 0xffff0000, v136
	v_lshlrev_b32_e32 v92, 16, v137
	v_and_b32_e32 v93, 0xffff0000, v137
	global_store_dwordx4 v[160:161], v[86:89], off offset:256
	s_waitcnt lgkmcnt(0)
	v_pk_fma_f32 v[84:85], v[84:85], v[90:91], v[192:193] op_sel_hi:[1,0,1]
	v_pk_fma_f32 v[82:83], v[82:83], v[90:91], v[220:221] op_sel_hi:[1,0,1]
	v_pk_fma_f32 v[86:87], v[80:81], v[90:91], v[194:195] op_sel_hi:[1,0,1]
	v_pk_fma_f32 v[80:81], v[78:79], v[90:91], v[222:223] op_sel_hi:[1,0,1]
	v_cvt_pk_bf16_f32 v78, v82, v83
	v_cvt_pk_bf16_f32 v79, v84, v85
	v_lshlrev_b32_e32 v124, 16, v134
	v_and_b32_e32 v125, 0xffff0000, v134
	v_lshlrev_b32_e32 v108, 16, v135
	v_and_b32_e32 v109, 0xffff0000, v135
	v_cvt_pk_bf16_f32 v80, v80, v81
	v_cvt_pk_bf16_f32 v81, v86, v87
	global_store_dwordx4 v[158:159], v[78:81], off
	v_pk_fma_f32 v[76:77], v[76:77], v[90:91], v[108:109] op_sel_hi:[1,0,1]
	v_pk_fma_f32 v[74:75], v[74:75], v[90:91], v[124:125] op_sel_hi:[1,0,1]
	v_pk_fma_f32 v[78:79], v[72:73], v[90:91], v[92:93] op_sel_hi:[1,0,1]
	v_pk_fma_f32 v[72:73], v[70:71], v[90:91], v[110:111] op_sel_hi:[1,0,1]
	v_cvt_pk_bf16_f32 v70, v74, v75
	v_cvt_pk_bf16_f32 v71, v76, v77
	v_add_co_u32_e32 v106, vcc, s53, v4
	v_cvt_pk_bf16_f32 v72, v72, v73
	v_cvt_pk_bf16_f32 v73, v78, v79
	global_store_dwordx4 v[158:159], v[70:73], off offset:256
	s_nop 0
	v_addc_co_u32_e32 v107, vcc, 0, v5, vcc
	global_load_dwordx4 v[78:81], v[106:107], off
	global_load_dwordx4 v[82:85], v[106:107], off offset:256
	v_add_co_u32_e32 v76, vcc, s54, v4
	s_waitcnt vmcnt(1)
	v_lshlrev_b32_e32 v108, 16, v78
	v_addc_co_u32_e32 v77, vcc, 0, v5, vcc
	global_load_dwordx4 v[86:89], v[76:77], off
	global_load_dwordx4 v[90:93], v[76:77], off offset:256
	v_add_co_u32_e32 v74, vcc, s55, v4
	v_and_b32_e32 v109, 0xffff0000, v78
	s_nop 0
	v_addc_co_u32_e32 v75, vcc, 0, v5, vcc
	global_load_dwordx4 v[94:97], v[74:75], off
	global_load_dwordx4 v[98:101], v[74:75], off offset:256
	v_add_co_u32_e32 v4, vcc, s56, v4
	v_lshlrev_b32_e32 v78, 16, v79
	s_nop 0
	v_addc_co_u32_e32 v5, vcc, 0, v5, vcc
	global_load_dwordx4 v[102:105], v[4:5], off
	global_load_dwordx4 v[70:73], v[4:5], off offset:256
	ds_read_b32 v134, v3 offset:1028
	v_and_b32_e32 v79, 0xffff0000, v79
	v_lshlrev_b32_e32 v110, 16, v80
	v_and_b32_e32 v111, 0xffff0000, v80
	v_lshlrev_b32_e32 v80, 16, v81
	v_and_b32_e32 v81, 0xffff0000, v81
	s_waitcnt vmcnt(6)
	v_lshlrev_b32_e32 v112, 16, v82
	v_and_b32_e32 v113, 0xffff0000, v82
	v_lshlrev_b32_e32 v114, 16, v84
	v_and_b32_e32 v115, 0xffff0000, v84
	v_lshlrev_b32_e32 v84, 16, v85
	v_and_b32_e32 v85, 0xffff0000, v85
	s_waitcnt lgkmcnt(0)
	v_pk_fma_f32 v[68:69], v[68:69], v[134:135], v[78:79] op_sel_hi:[1,0,1]
	v_pk_fma_f32 v[66:67], v[66:67], v[134:135], v[108:109] op_sel_hi:[1,0,1]
	v_pk_fma_f32 v[78:79], v[64:65], v[134:135], v[80:81] op_sel_hi:[1,0,1]
	v_pk_fma_f32 v[64:65], v[62:63], v[134:135], v[110:111] op_sel_hi:[1,0,1]
	v_cvt_pk_bf16_f32 v62, v66, v67
	v_cvt_pk_bf16_f32 v63, v68, v69
	v_lshlrev_b32_e32 v82, 16, v83
	v_and_b32_e32 v83, 0xffff0000, v83
	v_cvt_pk_bf16_f32 v64, v64, v65
	v_cvt_pk_bf16_f32 v65, v78, v79
	global_store_dwordx4 v[106:107], v[62:65], off
	v_pk_fma_f32 v[58:59], v[58:59], v[134:135], v[112:113] op_sel_hi:[1,0,1]
	v_pk_fma_f32 v[60:61], v[60:61], v[134:135], v[82:83] op_sel_hi:[1,0,1]
	v_pk_fma_f32 v[62:63], v[56:57], v[134:135], v[84:85] op_sel_hi:[1,0,1]
	v_pk_fma_f32 v[56:57], v[54:55], v[134:135], v[114:115] op_sel_hi:[1,0,1]
	v_cvt_pk_bf16_f32 v54, v58, v59
	v_cvt_pk_bf16_f32 v55, v60, v61
	s_andn2_b64 vcc, exec, s[6:7]
	v_cvt_pk_bf16_f32 v56, v56, v57
	v_cvt_pk_bf16_f32 v57, v62, v63
	ds_read_b32 v58, v3 offset:1156
	global_store_dwordx4 v[106:107], v[54:57], off offset:256
	s_waitcnt vmcnt(7)
; __device__ __forceinline__ float bflo(unsigned w) { return __uint_as_float(w << 16); }
; __device__ __forceinline__ float bfhi(unsigned w) { return __uint_as_float(w & 0xffff0000u); }
; #define PG8_BAR __builtin_amdgcn_s_barrier()
; template <class Epi, class Sched, bool ALIGN_EPI = false, bool SP2 = false>
; __device__ __forceinline__ void gemm_phase(PG8_LAS unsigned char* lds, const Gemm g, const Sched& S, const Epi& E) {
;     ...
;         if constexpr (!Epi::AFTER_DRAIN) { E(acc, cur, ui, wr, wc, fr, fq); S.done(cur); }
;         if (!has_next) break;
; #pragma unroll
;         for (int a = 0; a < 2; ++a)
; #pragma unroll
;             for (int b = 0; b < 2; ++b)
; #pragma unroll
;                 for (int m = 0; m < 4; ++m)
; #pragma unroll
;                     for (int n = 0; n < 2; ++n) acc[a][b][m][n] = (f32x4){0.f, 0.f, 0.f, 0.f};
;         cur = nxt; cA = nA; cB = nB; ++ui;
;         if constexpr (ALIGN_EPI) { if (wr == 1) PG8_BAR; }
;     }
;     __device__ __forceinline__ void operator()(const pg8::f32x4 (&acc)[2][2][4][2], const pg8::Unit& u, int ui, int wr, int wc, int fr, int fq) const {
;     ...
;             for (int m = 0; m < 4; ++m) { const size_t ro = off0 + (size_t)(ai * 128 + m * 16) * D;
; #pragma unroll
;                 for (int bj = 0; bj < 2; ++bj) {
;                     if (l == 0) { x[m][bj][0] = *(const pg8::f32x4*)(xin_p + ro + bj * 128); x[m][bj][1] = *(const pg8::f32x4*)(xin_p + ro + bj * 128 + 4); }
;                     else { const u32x4 w = *(const u32x4*)(xb + ro + bj * 128);
;                            x[m][bj][0] = (pg8::f32x4){bflo(w.x), bfhi(w.x), bflo(w.y), bfhi(w.y)}; x[m][bj][1] = (pg8::f32x4){bflo(w.z), bfhi(w.z), bflo(w.w), bfhi(w.w)}; } } }
; #pragma unroll
;             for (int m = 0; m < 4; ++m) { const size_t ro = off0 + (size_t)(ai * 128 + m * 16) * D; const float rB = tb[(ai * 128 + m * 16) * 2];
; #pragma unroll
;                 for (int bj = 0; bj < 2; ++bj) {
;                     const pg8::f32x4 y0 = x[m][bj][0] + acc[ai][bj][m][0] * rB, y1 = x[m][bj][1] + acc[ai][bj][m][1] * rB;
;                     u32x4 o; o.x = pg8::cvt_pk_bf16(y0[0], y0[1]); o.y = pg8::cvt_pk_bf16(y0[2], y0[3]); o.z = pg8::cvt_pk_bf16(y1[0], y1[1]); o.w = pg8::cvt_pk_bf16(y1[2], y1[3]);
;                     *(u32x4*)(xb + ro + bj * 128) = o; } }
	v_lshlrev_b32_e32 v116, 16, v86
	v_and_b32_e32 v117, 0xffff0000, v86
	v_lshlrev_b32_e32 v86, 16, v87
	v_and_b32_e32 v87, 0xffff0000, v87
	v_lshlrev_b32_e32 v118, 16, v88
	v_and_b32_e32 v119, 0xffff0000, v88
	v_lshlrev_b32_e32 v88, 16, v89
	v_and_b32_e32 v89, 0xffff0000, v89
	s_waitcnt vmcnt(6)
	v_lshlrev_b32_e32 v120, 16, v90
	v_and_b32_e32 v121, 0xffff0000, v90
	v_lshlrev_b32_e32 v122, 16, v92
	v_and_b32_e32 v123, 0xffff0000, v92
	v_lshlrev_b32_e32 v92, 16, v93
	v_and_b32_e32 v93, 0xffff0000, v93
	s_waitcnt lgkmcnt(0)
	v_pk_fma_f32 v[52:53], v[52:53], v[58:59], v[86:87] op_sel_hi:[1,0,1]
	v_pk_fma_f32 v[50:51], v[50:51], v[58:59], v[116:117] op_sel_hi:[1,0,1]
	v_pk_fma_f32 v[54:55], v[48:49], v[58:59], v[88:89] op_sel_hi:[1,0,1]
	v_pk_fma_f32 v[48:49], v[46:47], v[58:59], v[118:119] op_sel_hi:[1,0,1]
	v_cvt_pk_bf16_f32 v46, v50, v51
	v_cvt_pk_bf16_f32 v47, v52, v53
	v_lshlrev_b32_e32 v90, 16, v91
	v_and_b32_e32 v91, 0xffff0000, v91
	v_cvt_pk_bf16_f32 v48, v48, v49
	v_cvt_pk_bf16_f32 v49, v54, v55
	global_store_dwordx4 v[76:77], v[46:49], off
	v_pk_fma_f32 v[42:43], v[42:43], v[58:59], v[120:121] op_sel_hi:[1,0,1]
	v_pk_fma_f32 v[44:45], v[44:45], v[58:59], v[90:91] op_sel_hi:[1,0,1]
	v_pk_fma_f32 v[46:47], v[40:41], v[58:59], v[92:93] op_sel_hi:[1,0,1]
	v_pk_fma_f32 v[40:41], v[38:39], v[58:59], v[122:123] op_sel_hi:[1,0,1]
	v_cvt_pk_bf16_f32 v38, v42, v43
	v_cvt_pk_bf16_f32 v39, v44, v45
	s_waitcnt vmcnt(6)
	v_lshlrev_b32_e32 v124, 16, v94
	v_cvt_pk_bf16_f32 v40, v40, v41
	v_cvt_pk_bf16_f32 v41, v46, v47
	ds_read_b32 v42, v3 offset:1284
	v_and_b32_e32 v125, 0xffff0000, v94
	v_lshlrev_b32_e32 v94, 16, v95
	v_and_b32_e32 v95, 0xffff0000, v95
	v_lshlrev_b32_e32 v126, 16, v96
	v_and_b32_e32 v127, 0xffff0000, v96
	v_lshlrev_b32_e32 v96, 16, v97
	v_and_b32_e32 v97, 0xffff0000, v97
	s_waitcnt vmcnt(5)
	v_lshlrev_b32_e32 v128, 16, v98
	v_and_b32_e32 v129, 0xffff0000, v98
	v_lshlrev_b32_e32 v130, 16, v100
	v_and_b32_e32 v131, 0xffff0000, v100
	v_lshlrev_b32_e32 v100, 16, v101
	v_and_b32_e32 v101, 0xffff0000, v101
	global_store_dwordx4 v[76:77], v[38:41], off offset:256
	s_waitcnt lgkmcnt(0)
	v_pk_fma_f32 v[36:37], v[36:37], v[42:43], v[94:95] op_sel_hi:[1,0,1]
	v_pk_fma_f32 v[34:35], v[34:35], v[42:43], v[124:125] op_sel_hi:[1,0,1]
	v_pk_fma_f32 v[38:39], v[32:33], v[42:43], v[96:97] op_sel_hi:[1,0,1]
	v_pk_fma_f32 v[32:33], v[30:31], v[42:43], v[126:127] op_sel_hi:[1,0,1]
	v_cvt_pk_bf16_f32 v30, v34, v35
	v_cvt_pk_bf16_f32 v31, v36, v37
	v_lshlrev_b32_e32 v98, 16, v99
	v_and_b32_e32 v99, 0xffff0000, v99
	v_cvt_pk_bf16_f32 v32, v32, v33
	v_cvt_pk_bf16_f32 v33, v38, v39
	global_store_dwordx4 v[74:75], v[30:33], off
	v_pk_fma_f32 v[26:27], v[26:27], v[42:43], v[128:129] op_sel_hi:[1,0,1]
	v_pk_fma_f32 v[28:29], v[28:29], v[42:43], v[98:99] op_sel_hi:[1,0,1]
	v_pk_fma_f32 v[30:31], v[24:25], v[42:43], v[100:101] op_sel_hi:[1,0,1]
	v_pk_fma_f32 v[24:25], v[22:23], v[42:43], v[130:131] op_sel_hi:[1,0,1]
	v_cvt_pk_bf16_f32 v22, v26, v27
	v_cvt_pk_bf16_f32 v23, v28, v29
	s_waitcnt vmcnt(6)
	v_lshlrev_b32_e32 v132, 16, v102
	v_cvt_pk_bf16_f32 v24, v24, v25
	v_cvt_pk_bf16_f32 v25, v30, v31
	ds_read_b32 v26, v3 offset:1412
	v_and_b32_e32 v133, 0xffff0000, v102
	v_lshlrev_b32_e32 v102, 16, v103
	v_and_b32_e32 v103, 0xffff0000, v103
	v_lshlrev_b32_e32 v136, 16, v104
	v_and_b32_e32 v137, 0xffff0000, v104
	v_lshlrev_b32_e32 v104, 16, v105
	v_and_b32_e32 v105, 0xffff0000, v105
	s_waitcnt vmcnt(5)
	v_lshlrev_b32_e32 v46, 16, v72
	v_and_b32_e32 v47, 0xffff0000, v72
	v_lshlrev_b32_e32 v28, 16, v73
	v_and_b32_e32 v29, 0xffff0000, v73
	global_store_dwordx4 v[74:75], v[22:25], off offset:256
	s_waitcnt lgkmcnt(0)
	v_pk_fma_f32 v[20:21], v[20:21], v[26:27], v[102:103] op_sel_hi:[1,0,1]
	v_pk_fma_f32 v[18:19], v[18:19], v[26:27], v[132:133] op_sel_hi:[1,0,1]
	v_pk_fma_f32 v[22:23], v[16:17], v[26:27], v[104:105] op_sel_hi:[1,0,1]
	v_pk_fma_f32 v[16:17], v[14:15], v[26:27], v[136:137] op_sel_hi:[1,0,1]
	v_cvt_pk_bf16_f32 v14, v18, v19
	v_cvt_pk_bf16_f32 v15, v20, v21
	v_lshlrev_b32_e32 v60, 16, v70
	v_and_b32_e32 v61, 0xffff0000, v70
	v_lshlrev_b32_e32 v44, 16, v71
	v_and_b32_e32 v45, 0xffff0000, v71
	v_cvt_pk_bf16_f32 v16, v16, v17
	v_cvt_pk_bf16_f32 v17, v22, v23
	global_store_dwordx4 v[4:5], v[14:17], off
	v_pk_fma_f32 v[12:13], v[12:13], v[26:27], v[44:45] op_sel_hi:[1,0,1]
	v_pk_fma_f32 v[10:11], v[10:11], v[26:27], v[60:61] op_sel_hi:[1,0,1]
	v_pk_fma_f32 v[14:15], v[8:9], v[26:27], v[28:29] op_sel_hi:[1,0,1]
	v_pk_fma_f32 v[8:9], v[6:7], v[26:27], v[46:47] op_sel_hi:[1,0,1]
	v_cvt_pk_bf16_f32 v6, v10, v11
	v_cvt_pk_bf16_f32 v7, v12, v13
	s_nop 0
	v_cvt_pk_bf16_f32 v8, v8, v9
	v_cvt_pk_bf16_f32 v9, v14, v15
	global_store_dwordx4 v[4:5], v[6:9], off offset:256
	s_cbranch_vccnz .LBB0_1294
	s_andn2_b64 vcc, exec, s[12:13]
	s_cbranch_vccnz .LBB0_1293
	s_barrier
	s_branch .LBB0_1293

; __global__ void __launch_bounds__(NTHR, 2) fwd(Args a_in) {
	.amdhsa_kernel _Z3fwd4Args
		.amdhsa_group_segment_fixed_size 0
		.amdhsa_private_segment_fixed_size 0
		.amdhsa_kernarg_size 392
		.amdhsa_user_sgpr_count 2
		.amdhsa_user_sgpr_dispatch_ptr 0
		.amdhsa_user_sgpr_queue_ptr 0
		.amdhsa_user_sgpr_kernarg_segment_ptr 1
		.amdhsa_user_sgpr_dispatch_id 0
		.amdhsa_user_sgpr_kernarg_preload_length 0
		.amdhsa_user_sgpr_kernarg_preload_offset 0
		.amdhsa_user_sgpr_private_segment_size 0
		.amdhsa_uses_dynamic_stack 0
		.amdhsa_enable_private_segment 0
		.amdhsa_system_sgpr_workgroup_id_x 1
		.amdhsa_system_sgpr_workgroup_id_y 0
		.amdhsa_system_sgpr_workgroup_id_z 0
		.amdhsa_system_sgpr_workgroup_info 0
		.amdhsa_system_vgpr_workitem_id 0
		.amdhsa_next_free_vgpr 256
		.amdhsa_next_free_sgpr 98
		.amdhsa_accum_offset 256
		.amdhsa_reserve_vcc 1
		.amdhsa_float_round_mode_32 0
		.amdhsa_float_round_mode_16_64 0
		.amdhsa_float_denorm_mode_32 3
		.amdhsa_float_denorm_mode_16_64 3
		.amdhsa_dx10_clamp 1
		.amdhsa_ieee_mode 1
		.amdhsa_fp16_overflow 0
		.amdhsa_tg_split 0
		.amdhsa_exception_fp_ieee_invalid_op 0
		.amdhsa_exception_fp_denorm_src 0
		.amdhsa_exception_fp_ieee_div_zero 0
		.amdhsa_exception_fp_ieee_overflow 0
		.amdhsa_exception_fp_ieee_underflow 0
		.amdhsa_exception_fp_ieee_inexact 0
		.amdhsa_exception_int_div_zero 0
	.end_amdhsa_kernel

; __global__ void __launch_bounds__(NTHR, 2) fwd(Args a_in) {
amdhsa.kernels:
  - .agpr_count:     0
    .args:
      - .offset:         0
        .size:           136
        .value_kind:     by_value
      - .offset:         136
        .size:           4
        .value_kind:     hidden_block_count_x
      - .offset:         140
        .size:           4
        .value_kind:     hidden_block_count_y
      - .offset:         144
        .size:           4
        .value_kind:     hidden_block_count_z
      - .offset:         148
        .size:           2
        .value_kind:     hidden_group_size_x
      - .offset:         150
        .size:           2
        .value_kind:     hidden_group_size_y
      - .offset:         152
        .size:           2
        .value_kind:     hidden_group_size_z
      - .offset:         154
        .size:           2
        .value_kind:     hidden_remainder_x
      - .offset:         156
        .size:           2
        .value_kind:     hidden_remainder_y
      - .offset:         158
        .size:           2
        .value_kind:     hidden_remainder_z
      - .offset:         176
        .size:           8
        .value_kind:     hidden_global_offset_x
      - .offset:         184
        .size:           8
        .value_kind:     hidden_global_offset_y
      - .offset:         192
        .size:           8
        .value_kind:     hidden_global_offset_z
      - .offset:         200
        .size:           2
        .value_kind:     hidden_grid_dims
      - .offset:         256
        .size:           4
        .value_kind:     hidden_dynamic_lds_size
    .group_segment_fixed_size: 0
    .kernarg_segment_align: 8
    .kernarg_segment_size: 392
    .language:       OpenCL C
    .language_version:
      - 2
      - 0
    .max_flat_workgroup_size: 512
    .name:           _Z3fwd4Args
    .private_segment_fixed_size: 0
    .sgpr_count:     104
    .sgpr_spill_count: 137
    .symbol:         _Z3fwd4Args.kd
    .uniform_work_group_size: 1
    .uses_dynamic_stack: false
    .vgpr_count:     256
    .vgpr_spill_count: 0
    .wavefront_size: 64
